# residual phases: each wave takes rows of the M-tiles its own XCD owns in the GEMMs (1024*xcd + local + 256k) and stores the int8 XQ rows write-back so the next GEMM finds its A operand in the XCD L2
# speedup vs baseline: 1.0029x; 1.0029x over previous
; __device__ __forceinline__ void resid_rows(bf16* __restrict__ XB, const bf16* __restrict__ Y, const float* __restrict__ PART, const float* __restrict__ g, float* __restrict__ RS, ...
;     f32x4 gv[16];
; #pragma unroll
;     for (int j = 0; j < 16; ++j) gv[j] = *(const f32x4*)(g + (lane + 64 * j) * 4);
;     for (int m = gw; m < MTOK; m += NGW) {
;         const float pv = PART[(size_t)m * 64 + lane];
;         bf16* xrow = XB + (size_t)m * DM; const bf16* yrow = Y + (size_t)m * DM;
;         v2u xr[16], yr[16];
; #pragma unroll
;         for (int j = 0; j < 16; ++j) { xr[j] = *(const v2u*)(xrow + (lane + 64 * j) * 4); yr[j] = *(const v2u*)(yrow + (lane + 64 * j) * 4); }
.LBB0_812:
	s_lshr_b32 s76, s4, 8
	s_mul_i32 s77, s76, 0x300
	s_add_i32 s8, s8, s77
	s_lshl_b32 s76, s76, 10
	s_add_i32 s76, s76, 0x400
	s_movk_i32 s14, 0x100
	s_load_dwordx2 s[0:1], s[2:3], 0x10
	s_load_dwordx2 s[18:19], s[2:3], 0x88
	s_lshl_b32 s12, s22, 12
	s_waitcnt vmcnt(2)
	v_lshlrev_b32_e32 v64, 2, v82
	s_lshl_b64 s[4:5], s[12:13], 2
	v_add_u32_e32 v40, 0x400, v64
	v_add_u32_e32 v42, 0x500, v64
	v_add_u32_e32 v32, 0x600, v64
	v_add_u32_e32 v34, 0x700, v64
	v_add_u32_e32 v66, 0x800, v64
	v_add_u32_e32 v68, 0x900, v64
	v_add_u32_e32 v70, 0xa00, v64
	v_add_u32_e32 v72, 0xb00, v64
	v_add_u32_e32 v74, 0xc00, v64
	v_add_u32_e32 v76, 0xd00, v64
	v_add_u32_e32 v78, 0xe00, v64
	v_add_u32_e32 v80, 0xf00, v64
	s_waitcnt lgkmcnt(0)
	s_add_u32 s0, s0, s4
	v_ashrrev_i32_e32 v65, 31, v64
	v_ashrrev_i32_e32 v41, 31, v40
	v_ashrrev_i32_e32 v43, 31, v42
	v_ashrrev_i32_e32 v33, 31, v32
	v_ashrrev_i32_e32 v35, 31, v34
	v_ashrrev_i32_e32 v67, 31, v66
	v_ashrrev_i32_e32 v69, 31, v68
	v_ashrrev_i32_e32 v71, 31, v70
	v_ashrrev_i32_e32 v73, 31, v72
	v_ashrrev_i32_e32 v75, 31, v74
	v_ashrrev_i32_e32 v77, 31, v76
	v_ashrrev_i32_e32 v79, 31, v78
	v_ashrrev_i32_e32 v81, 31, v80
	s_addc_u32 s1, s1, s5
	v_lshl_add_u64 v[0:1], v[80:81], 2, s[0:1]
	v_lshl_add_u64 v[4:5], v[78:79], 2, s[0:1]
	v_lshl_add_u64 v[8:9], v[76:77], 2, s[0:1]
	v_lshl_add_u64 v[12:13], v[74:75], 2, s[0:1]
	v_lshl_add_u64 v[16:17], v[72:73], 2, s[0:1]
	v_lshl_add_u64 v[20:21], v[70:71], 2, s[0:1]
	v_lshl_add_u64 v[24:25], v[68:69], 2, s[0:1]
	v_lshl_add_u64 v[28:29], v[66:67], 2, s[0:1]
	v_lshl_add_u64 v[34:35], v[34:35], 2, s[0:1]
	v_lshl_add_u64 v[36:37], v[32:33], 2, s[0:1]
	v_lshl_add_u64 v[42:43], v[42:43], 2, s[0:1]
	v_lshl_add_u64 v[44:45], v[40:41], 2, s[0:1]
	s_waitcnt vmcnt(0)
	v_lshl_add_u64 v[60:61], v[64:65], 2, s[0:1]
	global_load_dwordx4 v[0:3], v[0:1], off
	s_nop 0
	global_load_dwordx4 v[4:7], v[4:5], off
	s_nop 0
	global_load_dwordx4 v[8:11], v[8:9], off
	s_nop 0
	global_load_dwordx4 v[12:15], v[12:13], off
	s_nop 0
	global_load_dwordx4 v[16:19], v[16:17], off
	s_nop 0
	global_load_dwordx4 v[20:23], v[20:21], off
	s_nop 0
	global_load_dwordx4 v[24:27], v[24:25], off
	s_nop 0
	global_load_dwordx4 v[28:31], v[28:29], off
	s_nop 0
	global_load_dwordx4 v[32:35], v[34:35], off
	s_nop 0
	global_load_dwordx4 v[36:39], v[36:37], off
	s_nop 0
	global_load_dwordx4 v[40:43], v[42:43], off
	s_nop 0
	global_load_dwordx4 v[44:47], v[44:45], off
	s_nop 0
	global_load_dwordx4 v[48:51], v[60:61], off offset:3072
	global_load_dwordx4 v[52:55], v[60:61], off offset:2048
	global_load_dwordx4 v[56:59], v[60:61], off offset:1024
	s_nop 0
	global_load_dwordx4 v[60:63], v[60:61], off
	s_ashr_i32 s9, s8, 31
	s_ashr_i32 s15, s14, 31
	s_lshl_b64 s[0:1], s[8:9], 13
	s_lshl_b64 s[22:23], s[8:9], 2
	s_lshl_b64 s[24:25], s[14:15], 2
	v_lshl_add_u64 v[64:65], v[64:65], 1, s[0:1]
	s_lshl_b64 s[26:27], s[14:15], 13
	v_lshl_add_u64 v[66:67], v[66:67], 1, s[0:1]
	v_lshl_add_u64 v[68:69], v[68:69], 1, s[0:1]
	v_lshl_add_u64 v[70:71], v[70:71], 1, s[0:1]
	v_lshl_add_u64 v[72:73], v[72:73], 1, s[0:1]
	v_lshl_add_u64 v[74:75], v[74:75], 1, s[0:1]
	v_lshl_add_u64 v[76:77], v[76:77], 1, s[0:1]
	v_lshl_add_u64 v[78:79], v[78:79], 1, s[0:1]
	v_lshl_add_u64 v[80:81], v[80:81], 1, s[0:1]
	s_lshl_b64 s[0:1], s[8:9], 12
	v_ashrrev_i32_e32 v83, 31, v82
	s_add_u32 s0, s0, 0x56800000
	s_addc_u32 s1, s1, 0
	v_lshlrev_b64 v[84:85], 2, v[82:83]
	v_cmp_eq_u32_e64 s[2:3], 0, v82
	v_lshl_add_u64 v[82:83], s[0:1], 0, v[84:85]
	s_lshl_b64 s[30:31], s[14:15], 12
	s_lshl_b64 s[0:1], s[8:9], 8
	s_add_u32 s0, s0, 0x400000
	s_addc_u32 s1, s1, 0
	v_lshl_add_u64 v[84:85], s[0:1], 0, v[84:85]
	s_lshl_b64 s[42:43], s[14:15], 8
	s_mov_b32 s7, 0x2d800000
	s_mov_b32 s9, 0x3e800000
	s_branch .LBB0_814
.LBB0_813:
	s_or_b64 exec, exec, s[16:17]
	s_add_i32 s8, s8, s14
	s_add_u32 s22, s22, s24
	s_addc_u32 s23, s23, s25
	v_lshl_add_u64 v[64:65], v[64:65], 0, s[26:27]
	v_lshl_add_u64 v[66:67], v[66:67], 0, s[26:27]
	v_lshl_add_u64 v[68:69], v[68:69], 0, s[26:27]
	v_lshl_add_u64 v[70:71], v[70:71], 0, s[26:27]
	v_lshl_add_u64 v[72:73], v[72:73], 0, s[26:27]
	v_lshl_add_u64 v[74:75], v[74:75], 0, s[26:27]
	v_lshl_add_u64 v[76:77], v[76:77], 0, s[26:27]
	v_lshl_add_u64 v[78:79], v[78:79], 0, s[26:27]
	v_lshl_add_u64 v[80:81], v[80:81], 0, s[26:27]
	v_lshl_add_u64 v[82:83], v[82:83], 0, s[30:31]
	s_cmp_lt_i32 s8, s76
	v_lshl_add_u64 v[84:85], v[84:85], 0, s[42:43]
	s_cbranch_scc0 .LBB0_818
; __device__ __forceinline__ void resid_rows(bf16* __restrict__ XB, const bf16* __restrict__ Y, const float* __restrict__ PART, const float* __restrict__ g, float* __restrict__ RS, ...
;     ...
;         const float pv = PART[(size_t)m * 64 + lane];
;         bf16* xrow = XB + (size_t)m * DM; const bf16* yrow = Y + (size_t)m * DM;
;         v2u xr[16], yr[16];
; #pragma unroll
;         for (int j = 0; j < 16; ++j) { xr[j] = *(const v2u*)(xrow + (lane + 64 * j) * 4); yr[j] = *(const v2u*)(yrow + (lane + 64 * j) * 4); }
;         const float ry = 1.0f / sqrtf(wave_sum(pv) * (1.0f / DM) + EPS);
.LBB0_814:
	v_lshl_add_u64 v[88:89], s[18:19], 0, v[64:65]
	v_lshl_add_u64 v[86:87], s[18:19], 0, v[84:85]
	v_add_co_u32_e32 v90, vcc, s7, v88
	s_mov_b64 s[4:5], 0x2d800200
	s_nop 0
	v_addc_co_u32_e32 v91, vcc, 0, v89, vcc
	global_load_dword v110, v[86:87], off
	global_load_dwordx2 v[172:173], v[90:91], off nt
	global_load_dwordx2 v[176:177], v[90:91], off offset:512 nt
	global_load_dwordx2 v[166:167], v[90:91], off offset:1024 nt
	v_add_co_u32_e32 v92, vcc, s9, v88
	v_lshl_add_u64 v[168:169], v[88:89], 0, s[4:5]
	s_nop 0
	v_addc_co_u32_e32 v93, vcc, 0, v89, vcc
	global_load_dwordx2 v[162:163], v[90:91], off offset:1536 nt
	global_load_dwordx2 v[154:155], v[90:91], off offset:2048 nt
	global_load_dwordx2 v[148:149], v[90:91], off offset:2560 nt
	global_load_dwordx2 v[142:143], v[90:91], off offset:3072 nt
	global_load_dwordx2 v[164:165], v[92:93], off offset:1536 nt
	global_load_dwordx2 v[158:159], v[92:93], off offset:2048 nt
	global_load_dwordx2 v[150:151], v[92:93], off offset:2560 nt
	global_load_dwordx2 v[144:145], v[92:93], off offset:3072 nt
	global_load_dwordx2 v[178:179], v[92:93], off nt
	global_load_dwordx2 v[180:181], v[92:93], off offset:512 nt
	global_load_dwordx2 v[182:183], v[92:93], off offset:1024 nt
	global_load_dwordx2 v[136:137], v[90:91], off offset:3584 nt
	s_mov_b64 s[4:5], 0x2d800400
	v_lshl_add_u64 v[160:161], v[88:89], 0, s[4:5]
	s_mov_b64 s[4:5], 0x2d800600
	v_lshl_add_u64 v[156:157], v[88:89], 0, s[4:5]
	s_mov_b64 s[4:5], 0x2d800800
	v_lshl_add_u64 v[152:153], v[88:89], 0, s[4:5]
	s_mov_b64 s[4:5], 0x2d800a00
	v_lshl_add_u64 v[146:147], v[88:89], 0, s[4:5]
	s_mov_b64 s[4:5], 0x2d800c00
	s_mov_b64 s[0:1], 0x2d800000
	v_lshl_add_u64 v[138:139], v[88:89], 0, s[4:5]
	s_mov_b64 s[4:5], 0x2d800e00
	v_lshl_add_u64 v[174:175], v[88:89], 0, s[0:1]
	v_lshl_add_u64 v[126:127], v[88:89], 0, s[4:5]
	v_lshl_add_u64 v[88:89], s[18:19], 0, v[66:67]
	v_add_co_u32_e32 v90, vcc, s7, v88
	v_lshl_add_u64 v[96:97], s[18:19], 0, v[68:69]
	s_nop 0
	v_addc_co_u32_e32 v91, vcc, 0, v89, vcc
	v_add_co_u32_e32 v94, vcc, s9, v88
	v_lshl_add_u64 v[86:87], v[88:89], 0, s[0:1]
	s_nop 0
	v_addc_co_u32_e32 v95, vcc, 0, v89, vcc
	v_add_co_u32_e32 v98, vcc, s7, v96
	v_lshl_add_u64 v[88:89], v[96:97], 0, s[0:1]
	s_nop 0
	v_addc_co_u32_e32 v99, vcc, 0, v97, vcc
	global_load_dwordx2 v[140:141], v[92:93], off offset:3584 nt
	global_load_dwordx2 v[130:131], v[90:91], off nt
	global_load_dwordx2 v[132:133], v[94:95], off nt
	global_load_dwordx2 v[122:123], v[98:99], off nt
	v_add_co_u32_e32 v94, vcc, s9, v96
	v_lshl_add_u64 v[92:93], s[18:19], 0, v[70:71]
	s_nop 0
	v_addc_co_u32_e32 v95, vcc, 0, v97, vcc
	v_add_co_u32_e32 v96, vcc, s7, v92
	v_lshl_add_u64 v[100:101], s[18:19], 0, v[72:73]
	s_nop 0
	v_addc_co_u32_e32 v97, vcc, 0, v93, vcc
	v_add_co_u32_e32 v98, vcc, s9, v92
	v_lshl_add_u64 v[90:91], v[92:93], 0, s[0:1]
	s_nop 0
	v_addc_co_u32_e32 v99, vcc, 0, v93, vcc
	v_add_co_u32_e32 v102, vcc, s7, v100
	v_lshl_add_u64 v[92:93], v[100:101], 0, s[0:1]
	s_nop 0
	v_addc_co_u32_e32 v103, vcc, 0, v101, vcc
	global_load_dwordx2 v[128:129], v[94:95], off nt
	global_load_dwordx2 v[114:115], v[96:97], off nt
	global_load_dwordx2 v[116:117], v[98:99], off nt
	global_load_dwordx2 v[106:107], v[102:103], off nt
	v_add_co_u32_e32 v98, vcc, s9, v100
	v_lshl_add_u64 v[96:97], s[18:19], 0, v[74:75]
	s_nop 0
	v_addc_co_u32_e32 v99, vcc, 0, v101, vcc
	v_add_co_u32_e32 v100, vcc, s7, v96
	v_lshl_add_u64 v[104:105], s[18:19], 0, v[76:77]
	s_nop 0
	v_addc_co_u32_e32 v101, vcc, 0, v97, vcc
	v_add_co_u32_e32 v102, vcc, s9, v96
	v_lshl_add_u64 v[94:95], v[96:97], 0, s[0:1]
	s_nop 0
	v_addc_co_u32_e32 v103, vcc, 0, v97, vcc
	v_add_co_u32_e32 v108, vcc, s7, v104
	s_waitcnt vmcnt(23)
	ds_swizzle_b32 v111, v110 offset:swizzle(SWAP,1)
	v_addc_co_u32_e32 v109, vcc, 0, v105, vcc
	global_load_dwordx2 v[134:135], v[98:99], off nt
	global_load_dwordx2 v[118:119], v[100:101], off nt
	global_load_dwordx2 v[120:121], v[102:103], off nt
	s_nop 0
	global_load_dwordx2 v[108:109], v[108:109], off nt
	v_add_co_u32_e32 v102, vcc, s9, v104
	s_waitcnt lgkmcnt(0)
	v_add_f32_e32 v110, v110, v111
	ds_swizzle_b32 v111, v110 offset:swizzle(SWAP,2)
	v_addc_co_u32_e32 v103, vcc, 0, v105, vcc
	v_lshl_add_u64 v[98:99], s[18:19], 0, v[78:79]
	v_lshl_add_u64 v[96:97], v[104:105], 0, s[0:1]
	s_waitcnt lgkmcnt(0)
	v_add_f32_e32 v110, v110, v111
	ds_swizzle_b32 v111, v110 offset:swizzle(SWAP,4)
	v_add_co_u32_e32 v104, vcc, s7, v98
	v_lshl_add_u64 v[170:171], s[18:19], 0, v[80:81]
	s_nop 0
	v_addc_co_u32_e32 v105, vcc, 0, v99, vcc
	s_waitcnt lgkmcnt(0)
	v_add_f32_e32 v110, v110, v111
	ds_swizzle_b32 v111, v110 offset:swizzle(SWAP,8)
	v_add_co_u32_e32 v112, vcc, s9, v98
	v_lshl_add_u64 v[100:101], v[98:99], 0, s[0:1]
	s_nop 0
	v_addc_co_u32_e32 v113, vcc, 0, v99, vcc
	s_waitcnt lgkmcnt(0)
	v_add_f32_e32 v110, v110, v111
	ds_swizzle_b32 v111, v110 offset:swizzle(SWAP,16)
	v_add_co_u32_e32 v184, vcc, s7, v170
	v_lshl_add_u64 v[98:99], v[170:171], 0, s[0:1]
	s_nop 0
	v_addc_co_u32_e32 v185, vcc, 0, v171, vcc
	s_waitcnt lgkmcnt(0)
; template <int OFF = 0, class V> __device__ __forceinline__ void st_wt16(void* p, V v) { static_assert(sizeof(V) == 16, ""); asm volatile("global_store_dwordx4 %0, %1, off offset:%2 sc1\n\ts_nop 1" :: "v"(p), "v"(v), "i"(OFF)); }
; template <int OFF = 0, class V> __device__ __forceinline__ void st_wt8(void* p, V v) { static_assert(sizeof(V) == 8, ""); asm volatile("global_store_dwordx2 %0, %1, off offset:%2 sc1\n\ts_nop 1" :: "v"(p), "v"(v), "i"(OFF)); }
; __device__ __forceinline__ unsigned pk2(float lo, float hi) { return pg8::cvt_pk_bf16(lo, hi); }
; __device__ __forceinline__ float bf_lo(unsigned w) { return __uint_as_float(w << 16); }
; __device__ __forceinline__ float bf_hi(unsigned w) { return __uint_as_float(w & 0xffff0000u); }
; __device__ __forceinline__ void resid_rows(bf16* __restrict__ XB, const bf16* __restrict__ Y, const float* __restrict__ PART, const float* __restrict__ g, float* __restrict__ RS, ...
;     ...
;         const float ry = 1.0f / sqrtf(wave_sum(pv) * (1.0f / DM) + EPS);
;         float ss = 0.f, am = 0.f; f32x4 ov[16];
; #pragma unroll
;         for (int j = 0; j < 16; ++j) { const int c = (lane + 64 * j) * 4;
;             f32x4 o; o.x = bf_lo(xr[j].x) + bf_lo(yr[j].x) * ry * gv[j].x; o.y = bf_hi(xr[j].x) + bf_hi(yr[j].x) * ry * gv[j].y; o.z = bf_lo(xr[j].y) + bf_lo(yr[j].y) * ry * gv[j].z; o.w = bf_hi(xr[j].y) + bf_hi(yr[j].y) * ry * gv[j].w;
;             ss += (o.x * o.x + o.y * o.y) + (o.z * o.z + o.w * o.w); ov[j] = o; am = fmaxf(fmaxf(am, fmaxf(fabsf(o.x), fabsf(o.y))), fmaxf(fabsf(o.z), fabsf(o.w)));
;             if (outf) st_wt16(outf + (size_t)m * DM + c, o); else { v2u ob; ob.x = pk2(o.x, o.y); ob.y = pk2(o.z, o.w); st_wt8(xrow + c, ob); } }
	v_add_f32_e32 v110, v110, v111
	v_mov_b32_e32 v111, v110
	s_nop 1
	v_permlane32_swap_b32_e32 v110, v111
	v_add_f32_e32 v110, v110, v111
	v_fmamk_f32 v110, v110, 0x39800000, v216
	s_mov_b32 s0, 0xf800000
	v_mul_f32_e32 v111, 0x4f800000, v110
	v_cmp_gt_f32_e32 vcc, s0, v110
	s_nop 1
	v_cndmask_b32_e32 v186, v110, v111, vcc
	v_sqrt_f32_e32 v187, v186
	global_load_dwordx2 v[124:125], v[102:103], off nt
	global_load_dwordx2 v[110:111], v[104:105], off nt
	s_nop 0
	global_load_dwordx2 v[112:113], v[112:113], off nt
	s_nop 0
	global_load_dwordx2 v[102:103], v[184:185], off nt
	v_add_u32_e32 v104, -1, v187
	v_fma_f32 v105, -v104, v187, v186
	v_cmp_ge_f32_e64 s[4:5], 0, v105
	v_add_u32_e32 v105, 1, v187
	v_fma_f32 v184, -v105, v187, v186
	v_cndmask_b32_e64 v104, v187, v104, s[4:5]
	v_cmp_lt_f32_e64 s[4:5], 0, v184
	s_nop 1
	v_cndmask_b32_e64 v104, v104, v105, s[4:5]
	v_mul_f32_e32 v105, 0x37800000, v104
	v_cndmask_b32_e32 v104, v104, v105, vcc
	v_cmp_class_f32_e32 vcc, v186, v239
	s_mov_b32 s4, 0x42fe0000
	s_nop 0
	v_cndmask_b32_e32 v184, v104, v186, vcc
	v_div_scale_f32 v185, s[0:1], v184, v184, 1.0
	v_rcp_f32_e32 v186, v185
	v_add_co_u32_e32 v104, vcc, s9, v170
	s_mov_b32 s0, 0x1e3ce508
	s_nop 0
	v_addc_co_u32_e32 v105, vcc, 0, v171, vcc
	v_fma_f32 v170, -v185, v186, 1.0
	v_fmac_f32_e32 v186, v170, v186
	v_div_scale_f32 v170, vcc, 1.0, v184, 1.0
	v_mul_f32_e32 v171, v170, v186
	v_fma_f32 v187, -v185, v171, v170
	v_fmac_f32_e32 v171, v187, v186
	v_fma_f32 v170, -v185, v171, v170
	v_div_fmas_f32 v170, v170, v186, v171
	v_div_fixup_f32 v184, v170, v184, 1.0
	s_waitcnt vmcnt(19)
	v_lshlrev_b32_e32 v171, 16, v178
	v_lshlrev_b32_e32 v170, 16, v172
	v_mul_f32_e32 v171, v184, v171
	v_fmac_f32_e32 v170, v60, v171
	v_and_b32_e32 v171, 0xffff0000, v172
	v_and_b32_e32 v172, 0xffff0000, v178
	v_mul_f32_e32 v172, v184, v172
	v_lshlrev_b32_e32 v178, 16, v179
	v_fmac_f32_e32 v171, v61, v172
	v_lshlrev_b32_e32 v172, 16, v173
	v_mul_f32_e32 v178, v184, v178
	v_fmac_f32_e32 v172, v62, v178
	v_and_b32_e32 v178, 0xffff0000, v179
	v_and_b32_e32 v173, 0xffff0000, v173
	v_mul_f32_e32 v178, v184, v178
	v_fmac_f32_e32 v173, v63, v178
	v_max_f32_e64 v178, |v170|, |v171|
	v_max_f32_e64 v179, |v172|, |v173|
	global_load_dwordx2 v[104:105], v[104:105], off nt
	v_max3_f32 v185, v178, 0, v179
	v_cvt_pk_bf16_f32 v178, v170, v171
	v_cvt_pk_bf16_f32 v179, v172, v173
	s_nop 0
	global_store_dwordx2 v[174:175], v[178:179], off offset:0 sc1 nt
	s_nop 1
	s_waitcnt vmcnt(19)
	v_lshlrev_b32_e32 v175, 16, v180
	v_lshlrev_b32_e32 v174, 16, v176
	v_mul_f32_e32 v175, v184, v175
	v_fmac_f32_e32 v174, v56, v175
	v_and_b32_e32 v175, 0xffff0000, v176
	v_and_b32_e32 v176, 0xffff0000, v180
	v_mul_f32_e32 v176, v184, v176
	v_lshlrev_b32_e32 v178, 16, v181
	v_fmac_f32_e32 v175, v57, v176
	v_lshlrev_b32_e32 v176, 16, v177
	v_mul_f32_e32 v178, v184, v178
	v_fmac_f32_e32 v176, v58, v178
	v_and_b32_e32 v178, 0xffff0000, v181
	v_and_b32_e32 v177, 0xffff0000, v177
	v_mul_f32_e32 v178, v184, v178
	v_fmac_f32_e32 v177, v59, v178
	v_max_f32_e64 v178, |v174|, |v175|
	v_max_f32_e64 v179, |v176|, |v177|
	v_max3_f32 v180, v185, v178, v179
	v_cvt_pk_bf16_f32 v178, v174, v175
	v_cvt_pk_bf16_f32 v179, v176, v177
	s_nop 0
	global_store_dwordx2 v[168:169], v[178:179], off offset:0 sc1 nt
	s_nop 1
	s_waitcnt vmcnt(18)
	v_lshlrev_b32_e32 v169, 16, v182
	v_lshlrev_b32_e32 v168, 16, v166
	v_mul_f32_e32 v169, v184, v169
	v_fmac_f32_e32 v168, v52, v169
	v_and_b32_e32 v169, 0xffff0000, v182
	v_and_b32_e32 v166, 0xffff0000, v166
	v_mul_f32_e32 v169, v184, v169
	v_lshlrev_b32_e32 v178, 16, v183
	v_fmac_f32_e32 v166, v53, v169
	v_lshlrev_b32_e32 v169, 16, v167
	v_mul_f32_e32 v178, v184, v178
	v_fmac_f32_e32 v169, v54, v178
	v_and_b32_e32 v178, 0xffff0000, v183
	v_and_b32_e32 v167, 0xffff0000, v167
	v_mul_f32_e32 v178, v184, v178
	v_fmac_f32_e32 v167, v55, v178
	v_max_f32_e64 v178, |v168|, |v166|
	v_max_f32_e64 v179, |v169|, |v167|
	v_max3_f32 v180, v180, v178, v179
	v_cvt_pk_bf16_f32 v178, v168, v166
	v_cvt_pk_bf16_f32 v179, v169, v167
	s_nop 0
	global_store_dwordx2 v[160:161], v[178:179], off offset:0 sc1 nt
	s_nop 1
	v_lshlrev_b32_e32 v161, 16, v164
	v_lshlrev_b32_e32 v160, 16, v162
	v_mul_f32_e32 v161, v184, v161
	v_fmac_f32_e32 v160, v48, v161
	v_and_b32_e32 v161, 0xffff0000, v162
	v_and_b32_e32 v162, 0xffff0000, v164
	v_mul_f32_e32 v162, v184, v162
	v_lshlrev_b32_e32 v164, 16, v165
	v_fmac_f32_e32 v161, v49, v162
	v_lshlrev_b32_e32 v162, 16, v163
	v_mul_f32_e32 v164, v184, v164
	v_fmac_f32_e32 v162, v50, v164
	v_and_b32_e32 v164, 0xffff0000, v165
	v_and_b32_e32 v163, 0xffff0000, v163
	v_mul_f32_e32 v164, v184, v164
	v_fmac_f32_e32 v163, v51, v164
	v_max_f32_e64 v164, |v160|, |v161|
	v_max_f32_e64 v165, |v162|, |v163|
	v_max3_f32 v178, v180, v164, v165
	v_cvt_pk_bf16_f32 v164, v160, v161
	v_cvt_pk_bf16_f32 v165, v162, v163
	s_nop 0
	global_store_dwordx2 v[156:157], v[164:165], off offset:0 sc1 nt
	s_nop 1
	v_lshlrev_b32_e32 v157, 16, v158
	v_lshlrev_b32_e32 v156, 16, v154
	v_mul_f32_e32 v157, v184, v157
	v_fmac_f32_e32 v156, v44, v157
	v_and_b32_e32 v157, 0xffff0000, v158
	v_and_b32_e32 v154, 0xffff0000, v154
	v_mul_f32_e32 v157, v184, v157
	v_lshlrev_b32_e32 v158, 16, v159
	v_fmac_f32_e32 v154, v45, v157
	v_lshlrev_b32_e32 v157, 16, v155
	v_mul_f32_e32 v158, v184, v158
	v_fmac_f32_e32 v157, v46, v158
	v_and_b32_e32 v158, 0xffff0000, v159
	v_and_b32_e32 v155, 0xffff0000, v155
	v_mul_f32_e32 v158, v184, v158
	v_fmac_f32_e32 v155, v47, v158
	v_max_f32_e64 v158, |v156|, |v154|
	v_max_f32_e64 v159, |v157|, |v155|
	v_max3_f32 v164, v178, v158, v159
	v_cvt_pk_bf16_f32 v158, v156, v154
	v_cvt_pk_bf16_f32 v159, v157, v155
; template <int OFF = 0, class V> __device__ __forceinline__ void st_wt16(void* p, V v) { static_assert(sizeof(V) == 16, ""); asm volatile("global_store_dwordx4 %0, %1, off offset:%2 sc1\n\ts_nop 1" :: "v"(p), "v"(v), "i"(OFF)); }
; template <int OFF = 0, class V> __device__ __forceinline__ void st_wt8(void* p, V v) { static_assert(sizeof(V) == 8, ""); asm volatile("global_store_dwordx2 %0, %1, off offset:%2 sc1\n\ts_nop 1" :: "v"(p), "v"(v), "i"(OFF)); }
; __device__ __forceinline__ unsigned pk2(float lo, float hi) { return pg8::cvt_pk_bf16(lo, hi); }
; __device__ __forceinline__ float bf_lo(unsigned w) { return __uint_as_float(w << 16); }
; __device__ __forceinline__ float bf_hi(unsigned w) { return __uint_as_float(w & 0xffff0000u); }
; __device__ __forceinline__ void resid_rows(bf16* __restrict__ XB, const bf16* __restrict__ Y, const float* __restrict__ PART, const float* __restrict__ g, float* __restrict__ RS, ...
;     ...
;         for (int j = 0; j < 16; ++j) { const int c = (lane + 64 * j) * 4;
;             f32x4 o; o.x = bf_lo(xr[j].x) + bf_lo(yr[j].x) * ry * gv[j].x; o.y = bf_hi(xr[j].x) + bf_hi(yr[j].x) * ry * gv[j].y; o.z = bf_lo(xr[j].y) + bf_lo(yr[j].y) * ry * gv[j].z; o.w = bf_hi(xr[j].y) + bf_hi(yr[j].y) * ry * gv[j].w;
;             ss += (o.x * o.x + o.y * o.y) + (o.z * o.z + o.w * o.w); ov[j] = o; am = fmaxf(fmaxf(am, fmaxf(fabsf(o.x), fabsf(o.y))), fmaxf(fabsf(o.z), fabsf(o.w)));
;             if (outf) st_wt16(outf + (size_t)m * DM + c, o); else { v2u ob; ob.x = pk2(o.x, o.y); ob.y = pk2(o.z, o.w); st_wt8(xrow + c, ob); } }
	s_nop 0
	global_store_dwordx2 v[152:153], v[158:159], off offset:0 sc1 nt
	s_nop 1
	v_lshlrev_b32_e32 v153, 16, v150
	v_lshlrev_b32_e32 v152, 16, v148
	v_mul_f32_e32 v153, v184, v153
	v_and_b32_e32 v150, 0xffff0000, v150
	v_fmac_f32_e32 v152, v40, v153
	v_and_b32_e32 v148, 0xffff0000, v148
	v_mul_f32_e32 v150, v184, v150
	v_lshlrev_b32_e32 v153, 16, v151
	v_and_b32_e32 v151, 0xffff0000, v151
	v_fmac_f32_e32 v148, v41, v150
	v_lshlrev_b32_e32 v150, 16, v149
	v_mul_f32_e32 v153, v184, v153
	v_and_b32_e32 v149, 0xffff0000, v149
	v_mul_f32_e32 v151, v184, v151
	v_fmac_f32_e32 v150, v42, v153
	v_fmac_f32_e32 v149, v43, v151
	v_cvt_pk_bf16_f32 v158, v152, v148
	v_cvt_pk_bf16_f32 v159, v150, v149
	v_max_f32_e64 v151, |v152|, |v148|
	global_store_dwordx2 v[146:147], v[158:159], off offset:0 sc1 nt
	s_nop 1
	v_lshlrev_b32_e32 v147, 16, v144
	v_lshlrev_b32_e32 v146, 16, v142
	v_mul_f32_e32 v147, v184, v147
	v_and_b32_e32 v144, 0xffff0000, v144
	v_fmac_f32_e32 v146, v36, v147
	v_and_b32_e32 v142, 0xffff0000, v142
	v_mul_f32_e32 v144, v184, v144
	v_lshlrev_b32_e32 v147, 16, v145
	v_and_b32_e32 v145, 0xffff0000, v145
	v_fmac_f32_e32 v142, v37, v144
	v_lshlrev_b32_e32 v144, 16, v143
	v_mul_f32_e32 v147, v184, v147
	v_and_b32_e32 v143, 0xffff0000, v143
	v_mul_f32_e32 v145, v184, v145
	v_fmac_f32_e32 v144, v38, v147
	v_fmac_f32_e32 v143, v39, v145
	v_cvt_pk_bf16_f32 v158, v146, v142
	v_cvt_pk_bf16_f32 v159, v144, v143
	v_max_f32_e64 v153, |v150|, |v149|
	global_store_dwordx2 v[138:139], v[158:159], off offset:0 sc1 nt
	s_nop 1
	s_waitcnt vmcnt(16)
	v_lshlrev_b32_e32 v139, 16, v140
	v_lshlrev_b32_e32 v138, 16, v136
	v_mul_f32_e32 v139, v184, v139
	v_fmac_f32_e32 v138, v32, v139
	v_and_b32_e32 v139, 0xffff0000, v140
	v_and_b32_e32 v136, 0xffff0000, v136
	v_mul_f32_e32 v139, v184, v139
	v_lshlrev_b32_e32 v140, 16, v141
	v_fmac_f32_e32 v136, v33, v139
	v_lshlrev_b32_e32 v139, 16, v137
	v_mul_f32_e32 v140, v184, v140
	v_fmac_f32_e32 v139, v34, v140
	v_and_b32_e32 v140, 0xffff0000, v141
	v_and_b32_e32 v137, 0xffff0000, v137
	v_mul_f32_e32 v140, v184, v140
	v_max3_f32 v151, v164, v151, v153
	v_max_f32_e64 v145, |v146|, |v142|
	v_max_f32_e64 v147, |v144|, |v143|
	v_fmac_f32_e32 v137, v35, v140
	v_max3_f32 v145, v151, v145, v147
	v_max_f32_e64 v140, |v138|, |v136|
	v_max_f32_e64 v141, |v139|, |v137|
	v_max3_f32 v145, v145, v140, v141
	v_cvt_pk_bf16_f32 v140, v138, v136
	v_cvt_pk_bf16_f32 v141, v139, v137
	s_nop 0
	global_store_dwordx2 v[126:127], v[140:141], off offset:0 sc1 nt
	s_nop 1
	s_waitcnt vmcnt(14)
	v_lshlrev_b32_e32 v127, 16, v132
	v_lshlrev_b32_e32 v126, 16, v130
	v_mul_f32_e32 v127, v184, v127
	v_fmac_f32_e32 v126, v28, v127
	v_and_b32_e32 v127, 0xffff0000, v130
	v_and_b32_e32 v130, 0xffff0000, v132
	v_mul_f32_e32 v130, v184, v130
	v_lshlrev_b32_e32 v132, 16, v133
	v_fmac_f32_e32 v127, v29, v130
	v_lshlrev_b32_e32 v130, 16, v131
	v_mul_f32_e32 v132, v184, v132
	v_fmac_f32_e32 v130, v30, v132
	v_and_b32_e32 v132, 0xffff0000, v133
	v_and_b32_e32 v131, 0xffff0000, v131
	v_mul_f32_e32 v132, v184, v132
	v_fmac_f32_e32 v131, v31, v132
	v_max_f32_e64 v132, |v126|, |v127|
	v_max_f32_e64 v133, |v130|, |v131|
	s_waitcnt vmcnt(12)
	v_lshlrev_b32_e32 v141, 16, v128
	v_max3_f32 v133, v145, v132, v133
	v_lshlrev_b32_e32 v132, 16, v122
	v_mul_f32_e32 v141, v184, v141
	v_and_b32_e32 v128, 0xffff0000, v128
	v_fmac_f32_e32 v132, v24, v141
	v_and_b32_e32 v122, 0xffff0000, v122
	v_mul_f32_e32 v128, v184, v128
	v_lshlrev_b32_e32 v141, 16, v129
	v_and_b32_e32 v129, 0xffff0000, v129
	v_fmac_f32_e32 v122, v25, v128
	v_lshlrev_b32_e32 v128, 16, v123
	v_mul_f32_e32 v141, v184, v141
	v_and_b32_e32 v123, 0xffff0000, v123
	v_mul_f32_e32 v129, v184, v129
	v_fmac_f32_e32 v128, v26, v141
	v_fmac_f32_e32 v123, v27, v129
	v_max_f32_e64 v129, |v132|, |v122|
	v_max_f32_e64 v141, |v128|, |v123|
	v_max3_f32 v133, v133, v129, v141
	s_waitcnt vmcnt(10)
	v_lshlrev_b32_e32 v141, 16, v116
	v_lshlrev_b32_e32 v129, 16, v114
	v_mul_f32_e32 v141, v184, v141
	v_and_b32_e32 v116, 0xffff0000, v116
	v_fmac_f32_e32 v129, v20, v141
	v_and_b32_e32 v114, 0xffff0000, v114
	v_mul_f32_e32 v116, v184, v116
	v_lshlrev_b32_e32 v141, 16, v117
	v_and_b32_e32 v117, 0xffff0000, v117
	v_fmac_f32_e32 v114, v21, v116
	v_lshlrev_b32_e32 v116, 16, v115
	v_mul_f32_e32 v141, v184, v141
	v_and_b32_e32 v115, 0xffff0000, v115
	v_mul_f32_e32 v117, v184, v117
	v_fmac_f32_e32 v116, v22, v141
	v_fmac_f32_e32 v115, v23, v117
	v_max_f32_e64 v117, |v129|, |v114|
	v_max_f32_e64 v141, |v116|, |v115|
	v_max3_f32 v141, v133, v117, v141
	s_waitcnt vmcnt(8)
	v_lshlrev_b32_e32 v133, 16, v134
	v_lshlrev_b32_e32 v117, 16, v106
	v_mul_f32_e32 v133, v184, v133
	v_fmac_f32_e32 v117, v16, v133
	v_and_b32_e32 v133, 0xffff0000, v134
	v_and_b32_e32 v106, 0xffff0000, v106
	v_mul_f32_e32 v133, v184, v133
	v_lshlrev_b32_e32 v134, 16, v135
	v_fmac_f32_e32 v106, v17, v133
	v_lshlrev_b32_e32 v133, 16, v107
	v_mul_f32_e32 v134, v184, v134
	v_fmac_f32_e32 v133, v18, v134
	v_and_b32_e32 v134, 0xffff0000, v135
	v_and_b32_e32 v107, 0xffff0000, v107
	v_mul_f32_e32 v134, v184, v134
	v_fmac_f32_e32 v107, v19, v134
	v_max_f32_e64 v134, |v117|, |v106|
	v_max_f32_e64 v135, |v133|, |v107|
	v_max3_f32 v135, v141, v134, v135
	s_waitcnt vmcnt(6)
	v_lshlrev_b32_e32 v141, 16, v120
	v_lshlrev_b32_e32 v134, 16, v118
	v_mul_f32_e32 v141, v184, v141
	v_and_b32_e32 v120, 0xffff0000, v120
	v_fmac_f32_e32 v134, v12, v141
	v_and_b32_e32 v118, 0xffff0000, v118
	v_mul_f32_e32 v120, v184, v120
	v_lshlrev_b32_e32 v141, 16, v121
	v_and_b32_e32 v121, 0xffff0000, v121
	v_fmac_f32_e32 v118, v13, v120
	v_lshlrev_b32_e32 v120, 16, v119
	v_mul_f32_e32 v141, v184, v141
	v_and_b32_e32 v119, 0xffff0000, v119
	v_mul_f32_e32 v121, v184, v121
	v_fmac_f32_e32 v120, v14, v141
	v_fmac_f32_e32 v119, v15, v121
	v_max_f32_e64 v121, |v134|, |v118|
	v_max_f32_e64 v141, |v120|, |v119|
	v_max3_f32 v135, v135, v121, v141
	s_waitcnt vmcnt(4)
; template <int OFF = 0, class V> __device__ __forceinline__ void st_wt16(void* p, V v) { static_assert(sizeof(V) == 16, ""); asm volatile("global_store_dwordx4 %0, %1, off offset:%2 sc1\n\ts_nop 1" :: "v"(p), "v"(v), "i"(OFF)); }
; template <int OFF = 0, class V> __device__ __forceinline__ void st_wt8(void* p, V v) { static_assert(sizeof(V) == 8, ""); asm volatile("global_store_dwordx2 %0, %1, off offset:%2 sc1\n\ts_nop 1" :: "v"(p), "v"(v), "i"(OFF)); }
; __device__ __forceinline__ void st_wt4(void* p, unsigned v) { asm volatile("global_store_dword %0, %1, off sc1\n\ts_nop 1" :: "v"(p), "v"(v)); }
; __device__ __forceinline__ unsigned pk2(float lo, float hi) { return pg8::cvt_pk_bf16(lo, hi); }
; __device__ __forceinline__ float bf_lo(unsigned w) { return __uint_as_float(w << 16); }
; __device__ __forceinline__ float bf_hi(unsigned w) { return __uint_as_float(w & 0xffff0000u); }
; __device__ __forceinline__ void resid_rows(bf16* __restrict__ XB, const bf16* __restrict__ Y, const float* __restrict__ PART, const float* __restrict__ g, float* __restrict__ RS, ...
;     ...
;         for (int j = 0; j < 16; ++j) { const int c = (lane + 64 * j) * 4;
;             f32x4 o; o.x = bf_lo(xr[j].x) + bf_lo(yr[j].x) * ry * gv[j].x; o.y = bf_hi(xr[j].x) + bf_hi(yr[j].x) * ry * gv[j].y; o.z = bf_lo(xr[j].y) + bf_lo(yr[j].y) * ry * gv[j].z; o.w = bf_hi(xr[j].y) + bf_hi(yr[j].y) * ry * gv[j].w;
;             ss += (o.x * o.x + o.y * o.y) + (o.z * o.z + o.w * o.w); ov[j] = o; am = fmaxf(fmaxf(am, fmaxf(fabsf(o.x), fabsf(o.y))), fmaxf(fabsf(o.z), fabsf(o.w)));
;             if (outf) st_wt16(outf + (size_t)m * DM + c, o); else { v2u ob; ob.x = pk2(o.x, o.y); ob.y = pk2(o.z, o.w); st_wt8(xrow + c, ob); } }
;         if (XQ) {
;             am = fmaxf(wave_max(am), 1e-20f); const float qs = 127.0f / am;
; #pragma unroll
;             for (int j = 0; j < 16; ++j) { const int q0 = (int)rintf(ov[j].x * qs), q1 = (int)rintf(ov[j].y * qs), q2 = (int)rintf(ov[j].z * qs), q3 = (int)rintf(ov[j].w * qs);
;                 st_wt4(XQ + (size_t)m * (DM / 4) + lane + 64 * j, ((unsigned)q0 & 255u) | (((unsigned)q1 & 255u) << 8) | (((unsigned)q2 & 255u) << 16) | ((unsigned)q3 << 24)); }
	v_lshlrev_b32_e32 v141, 16, v124
	v_lshlrev_b32_e32 v121, 16, v108
	v_mul_f32_e32 v141, v184, v141
	v_and_b32_e32 v124, 0xffff0000, v124
	v_fmac_f32_e32 v121, v8, v141
	v_and_b32_e32 v108, 0xffff0000, v108
	v_mul_f32_e32 v124, v184, v124
	v_lshlrev_b32_e32 v141, 16, v125
	v_and_b32_e32 v125, 0xffff0000, v125
	v_fmac_f32_e32 v108, v9, v124
	v_lshlrev_b32_e32 v124, 16, v109
	v_mul_f32_e32 v141, v184, v141
	v_and_b32_e32 v109, 0xffff0000, v109
	v_mul_f32_e32 v125, v184, v125
	v_fmac_f32_e32 v124, v10, v141
	v_fmac_f32_e32 v109, v11, v125
	v_max_f32_e64 v125, |v121|, |v108|
	v_max_f32_e64 v141, |v124|, |v109|
	v_max3_f32 v135, v135, v125, v141
	s_waitcnt vmcnt(2)
	v_lshlrev_b32_e32 v141, 16, v112
	v_lshlrev_b32_e32 v125, 16, v110
	v_mul_f32_e32 v141, v184, v141
	v_and_b32_e32 v112, 0xffff0000, v112
	v_fmac_f32_e32 v125, v4, v141
	v_and_b32_e32 v110, 0xffff0000, v110
	v_mul_f32_e32 v112, v184, v112
	v_lshlrev_b32_e32 v141, 16, v113
	v_and_b32_e32 v113, 0xffff0000, v113
	v_fmac_f32_e32 v110, v5, v112
	v_lshlrev_b32_e32 v112, 16, v111
	v_mul_f32_e32 v141, v184, v141
	v_and_b32_e32 v111, 0xffff0000, v111
	v_mul_f32_e32 v113, v184, v113
	v_fmac_f32_e32 v112, v6, v141
	v_fmac_f32_e32 v111, v7, v113
	v_max_f32_e64 v113, |v125|, |v110|
	v_max_f32_e64 v141, |v112|, |v111|
	v_max3_f32 v135, v135, v113, v141
	s_waitcnt vmcnt(0)
	v_lshlrev_b32_e32 v141, 16, v104
	v_lshlrev_b32_e32 v113, 16, v102
	v_mul_f32_e32 v141, v184, v141
	v_and_b32_e32 v104, 0xffff0000, v104
	v_fmac_f32_e32 v113, v0, v141
	v_and_b32_e32 v102, 0xffff0000, v102
	v_mul_f32_e32 v104, v184, v104
	v_lshlrev_b32_e32 v141, 16, v105
	v_and_b32_e32 v105, 0xffff0000, v105
	v_fmac_f32_e32 v102, v1, v104
	v_lshlrev_b32_e32 v104, 16, v103
	v_mul_f32_e32 v141, v184, v141
	v_and_b32_e32 v103, 0xffff0000, v103
	v_mul_f32_e32 v105, v184, v105
	v_fmac_f32_e32 v104, v2, v141
	v_fmac_f32_e32 v103, v3, v105
	v_max_f32_e64 v105, |v113|, |v102|
	v_max_f32_e64 v141, |v104|, |v103|
	v_max3_f32 v105, v135, v105, v141
	ds_swizzle_b32 v135, v105 offset:swizzle(SWAP,1)
	v_cvt_pk_bf16_f32 v140, v126, v127
	v_cvt_pk_bf16_f32 v141, v130, v131
	s_waitcnt lgkmcnt(0)
	v_max_f32_e32 v135, v135, v135
	v_max_f32_e32 v105, v105, v135
	ds_swizzle_b32 v135, v105 offset:swizzle(SWAP,2)
	global_store_dwordx2 v[86:87], v[140:141], off offset:0 sc1 nt
	s_nop 1
	v_cvt_pk_bf16_f32 v86, v132, v122
	v_cvt_pk_bf16_f32 v87, v128, v123
	s_nop 0
	global_store_dwordx2 v[88:89], v[86:87], off offset:0 sc1 nt
	s_nop 1
	v_cvt_pk_bf16_f32 v86, v129, v114
	v_cvt_pk_bf16_f32 v87, v116, v115
	s_nop 0
	global_store_dwordx2 v[90:91], v[86:87], off offset:0 sc1 nt
	s_nop 1
	s_waitcnt lgkmcnt(0)
	v_max_f32_e32 v86, v135, v135
	v_max_f32_e32 v88, v105, v86
	ds_swizzle_b32 v89, v88 offset:swizzle(SWAP,4)
	v_cvt_pk_bf16_f32 v86, v117, v106
	v_cvt_pk_bf16_f32 v87, v133, v107
	s_nop 0
	global_store_dwordx2 v[92:93], v[86:87], off offset:0 sc1 nt
	s_nop 1
	s_waitcnt lgkmcnt(0)
	v_max_f32_e32 v87, v89, v89
	v_max_f32_e32 v88, v88, v87
	ds_swizzle_b32 v89, v88 offset:swizzle(SWAP,8)
	v_cvt_pk_bf16_f32 v86, v134, v118
	v_cvt_pk_bf16_f32 v87, v120, v119
	s_waitcnt lgkmcnt(0)
	v_max_f32_e32 v89, v89, v89
	v_max_f32_e32 v88, v88, v89
	ds_swizzle_b32 v89, v88 offset:swizzle(SWAP,16)
	global_store_dwordx2 v[94:95], v[86:87], off offset:0 sc1 nt
	s_nop 1
	v_cvt_pk_bf16_f32 v86, v121, v108
	v_cvt_pk_bf16_f32 v87, v124, v109
	s_nop 0
	global_store_dwordx2 v[96:97], v[86:87], off offset:0 sc1 nt
	s_nop 1
	v_cvt_pk_bf16_f32 v86, v125, v110
	v_cvt_pk_bf16_f32 v87, v112, v111
	s_nop 0
	global_store_dwordx2 v[100:101], v[86:87], off offset:0 sc1 nt
	s_nop 1
	s_waitcnt lgkmcnt(0)
	v_max_f32_e32 v86, v89, v89
	v_max_f32_e32 v86, v88, v86
	v_mov_b32_e32 v87, v86
	s_nop 1
	v_permlane32_swap_b32_e32 v86, v87
	v_max3_f32 v88, v86, v87, s0
	v_div_scale_f32 v89, s[0:1], v88, v88, s4
	v_rcp_f32_e32 v90, v89
	v_cvt_pk_bf16_f32 v86, v113, v102
	v_cvt_pk_bf16_f32 v87, v104, v103
	s_mov_b32 s0, 0x40c0c00
	global_store_dwordx2 v[98:99], v[86:87], off offset:0 sc1 nt
	s_nop 1
	v_fma_f32 v86, -v89, v90, 1.0
	v_fmac_f32_e32 v90, v86, v90
	v_div_scale_f32 v86, vcc, s4, v88, s4
	v_mul_f32_e32 v87, v86, v90
	v_fma_f32 v91, -v89, v87, v86
	v_fmac_f32_e32 v87, v91, v90
	v_fma_f32 v86, -v89, v87, v86
	v_div_fmas_f32 v86, v86, v90, v87
	v_div_fixup_f32 v89, v86, v88, s4
	v_mul_f32_e32 v91, v171, v89
	v_mul_f32_e32 v90, v170, v89
	v_rndne_f32_e32 v91, v91
	v_mul_f32_e32 v92, v172, v89
	v_mul_f32_e32 v93, v173, v89
	v_rndne_f32_e32 v90, v90
	v_cvt_i32_f32_e32 v91, v91
	v_rndne_f32_e32 v92, v92
	v_rndne_f32_e32 v93, v93
	v_cvt_i32_f32_e32 v90, v90
	v_cvt_i32_f32_sdwa v92, v92 dst_sel:WORD_1 dst_unused:UNUSED_PAD src0_sel:DWORD
	v_cvt_i32_f32_e32 v93, v93
	v_lshlrev_b32_e32 v91, 8, v91
	v_and_b32_e32 v91, 0xff00, v91
	v_and_b32_e32 v92, 0xff0000, v92
	v_perm_b32 v90, v93, v90, s0
	v_or3_b32 v90, v90, v91, v92
	v_lshl_add_u64 v[86:87], s[18:19], 0, v[82:83]
	global_store_dword v[86:87], v90, off
	s_nop 1
	v_mul_f32_e32 v90, v174, v89
	v_rndne_f32_e32 v90, v90
	v_cvt_i32_f32_e32 v92, v90
	v_mul_f32_e32 v90, v175, v89
	v_rndne_f32_e32 v90, v90
	v_cvt_i32_f32_e32 v93, v90
	v_mul_f32_e32 v90, v176, v89
	v_rndne_f32_e32 v90, v90
	v_cvt_i32_f32_sdwa v94, v90 dst_sel:WORD_1 dst_unused:UNUSED_PAD src0_sel:DWORD
	v_mul_f32_e32 v90, v177, v89
	v_rndne_f32_e32 v90, v90
	v_cvt_i32_f32_e32 v95, v90
	s_mov_b64 s[4:5], 0x100
	v_lshlrev_b32_e32 v93, 8, v93
	v_lshl_add_u64 v[90:91], v[86:87], 0, s[4:5]
	v_and_b32_e32 v93, 0xff00, v93
	v_and_b32_e32 v94, 0xff0000, v94
	v_perm_b32 v92, v95, v92, s0
	v_or3_b32 v92, v92, v93, v94
	global_store_dword v[90:91], v92, off
	s_nop 1
	v_mul_f32_e32 v90, v168, v89
; __device__ __forceinline__ void st_wt4(void* p, unsigned v) { asm volatile("global_store_dword %0, %1, off sc1\n\ts_nop 1" :: "v"(p), "v"(v)); }
; __device__ __forceinline__ void resid_rows(bf16* __restrict__ XB, const bf16* __restrict__ Y, const float* __restrict__ PART, const float* __restrict__ g, float* __restrict__ RS, ...
;     ...
; #pragma unroll
;             for (int j = 0; j < 16; ++j) { const int q0 = (int)rintf(ov[j].x * qs), q1 = (int)rintf(ov[j].y * qs), q2 = (int)rintf(ov[j].z * qs), q3 = (int)rintf(ov[j].w * qs);
;                 st_wt4(XQ + (size_t)m * (DM / 4) + lane + 64 * j, ((unsigned)q0 & 255u) | (((unsigned)q1 & 255u) << 8) | (((unsigned)q2 & 255u) << 16) | ((unsigned)q3 << 24)); }
	v_rndne_f32_e32 v90, v90
	v_cvt_i32_f32_e32 v92, v90
	v_mul_f32_e32 v90, v166, v89
	v_rndne_f32_e32 v90, v90
	v_cvt_i32_f32_e32 v93, v90
	v_mul_f32_e32 v90, v169, v89
	v_rndne_f32_e32 v90, v90
	v_cvt_i32_f32_sdwa v94, v90 dst_sel:WORD_1 dst_unused:UNUSED_PAD src0_sel:DWORD
	v_mul_f32_e32 v90, v167, v89
	v_rndne_f32_e32 v90, v90
	v_cvt_i32_f32_e32 v95, v90
	s_mov_b64 s[4:5], 0x200
	v_lshlrev_b32_e32 v93, 8, v93
	v_lshl_add_u64 v[90:91], v[86:87], 0, s[4:5]
	v_and_b32_e32 v93, 0xff00, v93
	v_and_b32_e32 v94, 0xff0000, v94
	v_perm_b32 v92, v95, v92, s0
	v_or3_b32 v92, v92, v93, v94
	global_store_dword v[90:91], v92, off
	s_nop 1
	v_mul_f32_e32 v90, v160, v89
	v_rndne_f32_e32 v90, v90
	v_cvt_i32_f32_e32 v92, v90
	v_mul_f32_e32 v90, v161, v89
	v_rndne_f32_e32 v90, v90
	v_cvt_i32_f32_e32 v93, v90
	v_mul_f32_e32 v90, v162, v89
	v_rndne_f32_e32 v90, v90
	v_cvt_i32_f32_sdwa v94, v90 dst_sel:WORD_1 dst_unused:UNUSED_PAD src0_sel:DWORD
	v_mul_f32_e32 v90, v163, v89
	v_rndne_f32_e32 v90, v90
	v_cvt_i32_f32_e32 v95, v90
	s_mov_b64 s[4:5], 0x300
	v_lshlrev_b32_e32 v93, 8, v93
	v_lshl_add_u64 v[90:91], v[86:87], 0, s[4:5]
	v_and_b32_e32 v93, 0xff00, v93
	v_and_b32_e32 v94, 0xff0000, v94
	v_perm_b32 v92, v95, v92, s0
	v_or3_b32 v92, v92, v93, v94
	global_store_dword v[90:91], v92, off
	s_nop 1
	v_mul_f32_e32 v90, v156, v89
	v_rndne_f32_e32 v90, v90
	v_cvt_i32_f32_e32 v92, v90
	v_mul_f32_e32 v90, v154, v89
	v_rndne_f32_e32 v90, v90
	v_cvt_i32_f32_e32 v93, v90
	v_mul_f32_e32 v90, v157, v89
	v_rndne_f32_e32 v90, v90
	v_cvt_i32_f32_sdwa v94, v90 dst_sel:WORD_1 dst_unused:UNUSED_PAD src0_sel:DWORD
	v_mul_f32_e32 v90, v155, v89
	v_rndne_f32_e32 v90, v90
	v_cvt_i32_f32_e32 v95, v90
	s_mov_b64 s[4:5], 0x400
	v_lshlrev_b32_e32 v93, 8, v93
	v_lshl_add_u64 v[90:91], v[86:87], 0, s[4:5]
	v_and_b32_e32 v93, 0xff00, v93
	v_and_b32_e32 v94, 0xff0000, v94
	v_perm_b32 v92, v95, v92, s0
	v_or3_b32 v92, v92, v93, v94
	global_store_dword v[90:91], v92, off
	s_nop 1
	v_mul_f32_e32 v90, v152, v89
	v_rndne_f32_e32 v90, v90
	v_cvt_i32_f32_e32 v92, v90
	v_mul_f32_e32 v90, v148, v89
	v_rndne_f32_e32 v90, v90
	v_cvt_i32_f32_e32 v93, v90
	v_mul_f32_e32 v90, v150, v89
	v_rndne_f32_e32 v90, v90
	v_cvt_i32_f32_sdwa v94, v90 dst_sel:WORD_1 dst_unused:UNUSED_PAD src0_sel:DWORD
	v_mul_f32_e32 v90, v149, v89
	v_rndne_f32_e32 v90, v90
	v_cvt_i32_f32_e32 v95, v90
	s_mov_b64 s[4:5], 0x500
	v_lshlrev_b32_e32 v93, 8, v93
	v_lshl_add_u64 v[90:91], v[86:87], 0, s[4:5]
	v_and_b32_e32 v93, 0xff00, v93
	v_and_b32_e32 v94, 0xff0000, v94
	v_perm_b32 v92, v95, v92, s0
	v_or3_b32 v92, v92, v93, v94
	global_store_dword v[90:91], v92, off
	s_nop 1
	v_mul_f32_e32 v90, v146, v89
	v_rndne_f32_e32 v90, v90
	v_cvt_i32_f32_e32 v92, v90
	v_mul_f32_e32 v90, v142, v89
	v_rndne_f32_e32 v90, v90
	v_cvt_i32_f32_e32 v93, v90
	v_mul_f32_e32 v90, v144, v89
	v_rndne_f32_e32 v90, v90
	v_cvt_i32_f32_sdwa v94, v90 dst_sel:WORD_1 dst_unused:UNUSED_PAD src0_sel:DWORD
	v_mul_f32_e32 v90, v143, v89
	v_rndne_f32_e32 v90, v90
	v_cvt_i32_f32_e32 v95, v90
	s_mov_b64 s[4:5], 0x600
	v_lshlrev_b32_e32 v93, 8, v93
	v_lshl_add_u64 v[90:91], v[86:87], 0, s[4:5]
	v_and_b32_e32 v93, 0xff00, v93
	v_and_b32_e32 v94, 0xff0000, v94
	v_perm_b32 v92, v95, v92, s0
	v_or3_b32 v92, v92, v93, v94
	global_store_dword v[90:91], v92, off
	s_nop 1
	v_mul_f32_e32 v90, v138, v89
	v_rndne_f32_e32 v90, v90
	v_cvt_i32_f32_e32 v92, v90
	v_mul_f32_e32 v90, v136, v89
	v_rndne_f32_e32 v90, v90
	v_cvt_i32_f32_e32 v93, v90
	v_mul_f32_e32 v90, v139, v89
	v_rndne_f32_e32 v90, v90
	v_cvt_i32_f32_sdwa v94, v90 dst_sel:WORD_1 dst_unused:UNUSED_PAD src0_sel:DWORD
	v_mul_f32_e32 v90, v137, v89
	v_rndne_f32_e32 v90, v90
	v_cvt_i32_f32_e32 v95, v90
	s_mov_b64 s[4:5], 0x700
	v_lshlrev_b32_e32 v93, 8, v93
	v_lshl_add_u64 v[90:91], v[86:87], 0, s[4:5]
	v_and_b32_e32 v93, 0xff00, v93
	v_and_b32_e32 v94, 0xff0000, v94
	v_perm_b32 v92, v95, v92, s0
	v_or3_b32 v92, v92, v93, v94
	global_store_dword v[90:91], v92, off
	s_nop 1
	v_mul_f32_e32 v90, v126, v89
	v_rndne_f32_e32 v90, v90
	v_cvt_i32_f32_e32 v92, v90
	v_mul_f32_e32 v90, v127, v89
	v_rndne_f32_e32 v90, v90
	v_cvt_i32_f32_e32 v93, v90
	v_mul_f32_e32 v90, v130, v89
	v_rndne_f32_e32 v90, v90
	v_cvt_i32_f32_sdwa v94, v90 dst_sel:WORD_1 dst_unused:UNUSED_PAD src0_sel:DWORD
	v_mul_f32_e32 v90, v131, v89
	v_rndne_f32_e32 v90, v90
	v_cvt_i32_f32_e32 v95, v90
	s_mov_b64 s[4:5], 0x800
	v_lshlrev_b32_e32 v93, 8, v93
	v_lshl_add_u64 v[90:91], v[86:87], 0, s[4:5]
	v_and_b32_e32 v93, 0xff00, v93
	v_and_b32_e32 v94, 0xff0000, v94
	v_perm_b32 v92, v95, v92, s0
	v_or3_b32 v92, v92, v93, v94
	global_store_dword v[90:91], v92, off
	s_nop 1
	v_mul_f32_e32 v90, v132, v89
	v_rndne_f32_e32 v90, v90
	v_cvt_i32_f32_e32 v92, v90
	v_mul_f32_e32 v90, v122, v89
; __device__ __forceinline__ void st_wt4(void* p, unsigned v) { asm volatile("global_store_dword %0, %1, off sc1\n\ts_nop 1" :: "v"(p), "v"(v)); }
; __device__ __forceinline__ void resid_rows(bf16* __restrict__ XB, const bf16* __restrict__ Y, const float* __restrict__ PART, const float* __restrict__ g, float* __restrict__ RS, ...
;     ...
; #pragma unroll
;             for (int j = 0; j < 16; ++j) { const int q0 = (int)rintf(ov[j].x * qs), q1 = (int)rintf(ov[j].y * qs), q2 = (int)rintf(ov[j].z * qs), q3 = (int)rintf(ov[j].w * qs);
;                 st_wt4(XQ + (size_t)m * (DM / 4) + lane + 64 * j, ((unsigned)q0 & 255u) | (((unsigned)q1 & 255u) << 8) | (((unsigned)q2 & 255u) << 16) | ((unsigned)q3 << 24)); }
;             if (lane == 0) AS[m] = am * (1.0f / 127.0f); }
	v_rndne_f32_e32 v90, v90
	v_cvt_i32_f32_e32 v93, v90
	v_mul_f32_e32 v90, v128, v89
	v_rndne_f32_e32 v90, v90
	v_cvt_i32_f32_sdwa v94, v90 dst_sel:WORD_1 dst_unused:UNUSED_PAD src0_sel:DWORD
	v_mul_f32_e32 v90, v123, v89
	v_rndne_f32_e32 v90, v90
	v_cvt_i32_f32_e32 v95, v90
	s_mov_b64 s[4:5], 0x900
	v_lshlrev_b32_e32 v93, 8, v93
	v_lshl_add_u64 v[90:91], v[86:87], 0, s[4:5]
	v_and_b32_e32 v93, 0xff00, v93
	v_and_b32_e32 v94, 0xff0000, v94
	v_perm_b32 v92, v95, v92, s0
	v_or3_b32 v92, v92, v93, v94
	global_store_dword v[90:91], v92, off
	s_nop 1
	v_mul_f32_e32 v90, v129, v89
	v_rndne_f32_e32 v90, v90
	v_cvt_i32_f32_e32 v92, v90
	v_mul_f32_e32 v90, v114, v89
	v_rndne_f32_e32 v90, v90
	v_cvt_i32_f32_e32 v93, v90
	v_mul_f32_e32 v90, v116, v89
	v_rndne_f32_e32 v90, v90
	v_cvt_i32_f32_sdwa v94, v90 dst_sel:WORD_1 dst_unused:UNUSED_PAD src0_sel:DWORD
	v_mul_f32_e32 v90, v115, v89
	v_rndne_f32_e32 v90, v90
	v_cvt_i32_f32_e32 v95, v90
	s_mov_b64 s[4:5], 0xa00
	v_lshlrev_b32_e32 v93, 8, v93
	v_lshl_add_u64 v[90:91], v[86:87], 0, s[4:5]
	v_and_b32_e32 v93, 0xff00, v93
	v_and_b32_e32 v94, 0xff0000, v94
	v_perm_b32 v92, v95, v92, s0
	v_or3_b32 v92, v92, v93, v94
	global_store_dword v[90:91], v92, off
	s_nop 1
	v_mul_f32_e32 v90, v117, v89
	v_rndne_f32_e32 v90, v90
	v_cvt_i32_f32_e32 v92, v90
	v_mul_f32_e32 v90, v106, v89
	v_rndne_f32_e32 v90, v90
	v_cvt_i32_f32_e32 v93, v90
	v_mul_f32_e32 v90, v133, v89
	v_rndne_f32_e32 v90, v90
	v_cvt_i32_f32_sdwa v94, v90 dst_sel:WORD_1 dst_unused:UNUSED_PAD src0_sel:DWORD
	v_mul_f32_e32 v90, v107, v89
	v_rndne_f32_e32 v90, v90
	v_cvt_i32_f32_e32 v95, v90
	s_mov_b64 s[4:5], 0xb00
	v_lshlrev_b32_e32 v93, 8, v93
	v_lshl_add_u64 v[90:91], v[86:87], 0, s[4:5]
	v_and_b32_e32 v93, 0xff00, v93
	v_and_b32_e32 v94, 0xff0000, v94
	v_perm_b32 v92, v95, v92, s0
	v_or3_b32 v92, v92, v93, v94
	global_store_dword v[90:91], v92, off
	s_nop 1
	v_mul_f32_e32 v90, v134, v89
	v_rndne_f32_e32 v90, v90
	v_cvt_i32_f32_e32 v92, v90
	v_mul_f32_e32 v90, v118, v89
	v_rndne_f32_e32 v90, v90
	v_cvt_i32_f32_e32 v93, v90
	v_mul_f32_e32 v90, v120, v89
	v_rndne_f32_e32 v90, v90
	v_cvt_i32_f32_sdwa v94, v90 dst_sel:WORD_1 dst_unused:UNUSED_PAD src0_sel:DWORD
	v_mul_f32_e32 v90, v119, v89
	v_rndne_f32_e32 v90, v90
	v_cvt_i32_f32_e32 v95, v90
	s_mov_b64 s[4:5], 0xc00
	v_lshlrev_b32_e32 v93, 8, v93
	v_lshl_add_u64 v[90:91], v[86:87], 0, s[4:5]
	v_and_b32_e32 v93, 0xff00, v93
	v_and_b32_e32 v94, 0xff0000, v94
	v_perm_b32 v92, v95, v92, s0
	v_or3_b32 v92, v92, v93, v94
	global_store_dword v[90:91], v92, off
	s_nop 1
	v_mul_f32_e32 v90, v121, v89
	v_rndne_f32_e32 v90, v90
	v_cvt_i32_f32_e32 v92, v90
	v_mul_f32_e32 v90, v108, v89
	v_rndne_f32_e32 v90, v90
	v_cvt_i32_f32_e32 v93, v90
	v_mul_f32_e32 v90, v124, v89
	v_rndne_f32_e32 v90, v90
	v_cvt_i32_f32_sdwa v94, v90 dst_sel:WORD_1 dst_unused:UNUSED_PAD src0_sel:DWORD
	v_mul_f32_e32 v90, v109, v89
	v_rndne_f32_e32 v90, v90
	v_cvt_i32_f32_e32 v95, v90
	s_mov_b64 s[4:5], 0xd00
	v_lshlrev_b32_e32 v93, 8, v93
	v_lshl_add_u64 v[90:91], v[86:87], 0, s[4:5]
	v_and_b32_e32 v93, 0xff00, v93
	v_and_b32_e32 v94, 0xff0000, v94
	v_perm_b32 v92, v95, v92, s0
	v_or3_b32 v92, v92, v93, v94
	global_store_dword v[90:91], v92, off
	s_nop 1
	v_mul_f32_e32 v90, v125, v89
	v_rndne_f32_e32 v90, v90
	v_cvt_i32_f32_e32 v92, v90
	v_mul_f32_e32 v90, v110, v89
	v_rndne_f32_e32 v90, v90
	v_cvt_i32_f32_e32 v93, v90
	v_mul_f32_e32 v90, v112, v89
	v_rndne_f32_e32 v90, v90
	v_cvt_i32_f32_sdwa v94, v90 dst_sel:WORD_1 dst_unused:UNUSED_PAD src0_sel:DWORD
	v_mul_f32_e32 v90, v111, v89
	v_rndne_f32_e32 v90, v90
	v_cvt_i32_f32_e32 v95, v90
	s_mov_b64 s[4:5], 0xe00
	v_lshlrev_b32_e32 v93, 8, v93
	v_lshl_add_u64 v[90:91], v[86:87], 0, s[4:5]
	v_and_b32_e32 v93, 0xff00, v93
	v_and_b32_e32 v94, 0xff0000, v94
	v_perm_b32 v92, v95, v92, s0
	v_or3_b32 v92, v92, v93, v94
	global_store_dword v[90:91], v92, off
	s_nop 1
	v_mul_f32_e32 v91, v102, v89
	v_mul_f32_e32 v90, v113, v89
	v_rndne_f32_e32 v91, v91
	v_mul_f32_e32 v92, v104, v89
	v_mul_f32_e32 v89, v103, v89
	v_rndne_f32_e32 v90, v90
	v_cvt_i32_f32_e32 v91, v91
	v_rndne_f32_e32 v92, v92
	v_rndne_f32_e32 v89, v89
	v_cvt_i32_f32_e32 v90, v90
	v_cvt_i32_f32_sdwa v92, v92 dst_sel:WORD_1 dst_unused:UNUSED_PAD src0_sel:DWORD
	v_cvt_i32_f32_e32 v89, v89
	v_lshlrev_b32_e32 v91, 8, v91
	s_mov_b64 s[4:5], 0xf00
	v_and_b32_e32 v91, 0xff00, v91
	v_and_b32_e32 v92, 0xff0000, v92
	v_perm_b32 v89, v89, v90, s0
	v_lshl_add_u64 v[86:87], v[86:87], 0, s[4:5]
	v_or3_b32 v89, v89, v91, v92
	global_store_dword v[86:87], v89, off
	s_nop 1
	s_and_saveexec_b64 s[4:5], s[2:3]
	s_cbranch_execz .LBB0_816
	s_add_u32 s0, s18, s22
	v_mul_f32_e32 v86, 0x3c010204, v88
	s_addc_u32 s1, s19, s23
	v_mov_b32_e32 v87, 0x110000
	global_store_dword v87, v86, s[0:1]

; __device__ __forceinline__ void resid_rows(bf16* __restrict__ XB, const bf16* __restrict__ Y, const float* __restrict__ PART, const float* __restrict__ g, float* __restrict__ RS, ...
;     f32x4 gv[16];
; #pragma unroll
;     for (int j = 0; j < 16; ++j) gv[j] = *(const f32x4*)(g + (lane + 64 * j) * 4);
;     for (int m = gw; m < MTOK; m += NGW) {
;         const float pv = PART[(size_t)m * 64 + lane];
;         bf16* xrow = XB + (size_t)m * DM; const bf16* yrow = Y + (size_t)m * DM;
;         v2u xr[16], yr[16];
; #pragma unroll
;         for (int j = 0; j < 16; ++j) { xr[j] = *(const v2u*)(xrow + (lane + 64 * j) * 4); yr[j] = *(const v2u*)(yrow + (lane + 64 * j) * 4); }
.LBB0_1054:
	s_add_i32 s14, s7, s1
	s_cmpk_gt_i32 s14, 0x1fff
	s_cbranch_scc1 .LBB0_1128
	s_lshl_b32 s12, s22, 12
	v_lshlrev_b32_e32 v128, 2, v64
	s_lshr_b32 s76, s7, 8
	s_mul_i32 s77, s76, 0x300
	s_add_i32 s14, s14, s77
	s_lshl_b32 s76, s76, 10
	s_add_i32 s76, s76, 0x400
	s_movk_i32 s18, 0x100
	s_lshl_b64 s[0:1], s[12:13], 2
	v_add_u32_e32 v130, 0x400, v128
	v_add_u32_e32 v132, 0x500, v128
	v_add_u32_e32 v134, 0x600, v128
	v_add_u32_e32 v136, 0x700, v128
	v_add_u32_e32 v138, 0x800, v128
	v_add_u32_e32 v140, 0x900, v128
	v_add_u32_e32 v142, 0xa00, v128
	v_add_u32_e32 v144, 0xb00, v128
	v_add_u32_e32 v146, 0xc00, v128
	v_add_u32_e32 v148, 0xd00, v128
	v_add_u32_e32 v150, 0xe00, v128
	v_add_u32_e32 v152, 0xf00, v128
	s_waitcnt lgkmcnt(0)
	s_add_u32 s0, s2, s0
	v_ashrrev_i32_e32 v129, 31, v128
	v_ashrrev_i32_e32 v131, 31, v130
	v_ashrrev_i32_e32 v133, 31, v132
	v_ashrrev_i32_e32 v135, 31, v134
	v_ashrrev_i32_e32 v137, 31, v136
	v_ashrrev_i32_e32 v139, 31, v138
	v_ashrrev_i32_e32 v141, 31, v140
	v_ashrrev_i32_e32 v143, 31, v142
	v_ashrrev_i32_e32 v145, 31, v144
	v_ashrrev_i32_e32 v147, 31, v146
	v_ashrrev_i32_e32 v149, 31, v148
	v_ashrrev_i32_e32 v151, 31, v150
	v_ashrrev_i32_e32 v153, 31, v152
	s_addc_u32 s1, s3, s1
	v_lshl_add_u64 v[0:1], v[152:153], 2, s[0:1]
	v_lshl_add_u64 v[4:5], v[150:151], 2, s[0:1]
	v_lshl_add_u64 v[8:9], v[148:149], 2, s[0:1]
	v_lshl_add_u64 v[12:13], v[146:147], 2, s[0:1]
	v_lshl_add_u64 v[16:17], v[144:145], 2, s[0:1]
	v_lshl_add_u64 v[20:21], v[142:143], 2, s[0:1]
	v_lshl_add_u64 v[24:25], v[140:141], 2, s[0:1]
	v_lshl_add_u64 v[28:29], v[138:139], 2, s[0:1]
	v_lshl_add_u64 v[32:33], v[136:137], 2, s[0:1]
	v_lshl_add_u64 v[36:37], v[134:135], 2, s[0:1]
	v_lshl_add_u64 v[40:41], v[132:133], 2, s[0:1]
	v_lshl_add_u64 v[44:45], v[130:131], 2, s[0:1]
	v_lshl_add_u64 v[60:61], v[128:129], 2, s[0:1]
	global_load_dwordx4 v[0:3], v[0:1], off
	s_nop 0
	global_load_dwordx4 v[4:7], v[4:5], off
	s_nop 0
	global_load_dwordx4 v[8:11], v[8:9], off
	s_nop 0
	global_load_dwordx4 v[12:15], v[12:13], off
	s_nop 0
	global_load_dwordx4 v[16:19], v[16:17], off
	s_nop 0
	global_load_dwordx4 v[20:23], v[20:21], off
	s_nop 0
	global_load_dwordx4 v[24:27], v[24:25], off
	s_nop 0
	global_load_dwordx4 v[28:31], v[28:29], off
	s_nop 0
	global_load_dwordx4 v[32:35], v[32:33], off
	s_nop 0
	global_load_dwordx4 v[36:39], v[36:37], off
	s_nop 0
	global_load_dwordx4 v[40:43], v[40:41], off
	s_nop 0
	global_load_dwordx4 v[44:47], v[44:45], off
	s_nop 0
	global_load_dwordx4 v[48:51], v[60:61], off offset:3072
	global_load_dwordx4 v[52:55], v[60:61], off offset:2048
	global_load_dwordx4 v[56:59], v[60:61], off offset:1024
	s_nop 0
	global_load_dwordx4 v[60:63], v[60:61], off
	s_add_u32 s2, s8, 0x56800000
	v_readlane_b32 s0, v254, 37
	s_addc_u32 s3, s9, 0
	v_readlane_b32 s1, v254, 38
	s_and_b64 s[0:1], s[0:1], exec
	s_cselect_b32 s7, 0, s3
	s_cselect_b32 s12, 0, s2
	s_cmp_lg_u64 s[4:5], 0
	s_cselect_b64 s[0:1], -1, 0
	s_ashr_i32 s15, s14, 31
	s_ashr_i32 s19, s18, 31
	s_lshl_b64 s[10:11], s[14:15], 13
	s_lshl_b64 s[22:23], s[14:15], 2
	s_lshl_b64 s[24:25], s[18:19], 2
	v_lshl_add_u64 v[154:155], v[128:129], 1, s[10:11]
	s_lshl_b64 s[26:27], s[18:19], 13
	v_lshl_add_u64 v[156:157], v[138:139], 1, s[10:11]
	v_lshl_add_u64 v[158:159], v[140:141], 1, s[10:11]
	v_lshl_add_u64 v[160:161], v[142:143], 1, s[10:11]
	v_lshl_add_u64 v[162:163], v[144:145], 1, s[10:11]
	v_lshl_add_u64 v[164:165], v[146:147], 1, s[10:11]
	v_lshl_add_u64 v[166:167], v[148:149], 1, s[10:11]
	v_lshl_add_u64 v[168:169], v[150:151], 1, s[10:11]
	v_lshl_add_u64 v[170:171], v[152:153], 1, s[10:11]
	s_lshl_b64 s[10:11], s[14:15], 14
	s_add_u32 s30, s4, s10
	s_addc_u32 s31, s5, s11
	s_lshl_b64 s[36:37], s[18:19], 14
	s_lshl_b64 s[4:5], s[14:15], 12
	v_ashrrev_i32_e32 v65, 31, v64
	s_add_u32 s4, s12, s4
	v_cmp_eq_u32_e64 s[2:3], 0, v64
	v_lshlrev_b64 v[64:65], 2, v[64:65]
	s_addc_u32 s5, s7, s5
	v_lshl_add_u64 v[172:173], s[4:5], 0, v[64:65]
	s_lshl_b64 s[42:43], s[18:19], 12
	s_lshl_b64 s[4:5], s[14:15], 8
	s_add_u32 s4, s4, 0x400000
	s_addc_u32 s5, s5, 0
	v_lshl_add_u64 v[174:175], s[4:5], 0, v[64:65]
	s_lshl_b64 s[44:45], s[18:19], 8
	s_mov_b32 s12, 0x2d800000
	s_mov_b32 s15, 0x3e800000
	s_branch .LBB0_1057
.LBB0_1056:
	s_or_b64 exec, exec, s[16:17]
	s_add_i32 s14, s14, s18
	s_add_u32 s22, s22, s24
	s_addc_u32 s23, s23, s25
	s_add_u32 s30, s30, s36
	s_addc_u32 s31, s31, s37
	v_lshl_add_u64 v[154:155], v[154:155], 0, s[26:27]
	v_lshl_add_u64 v[156:157], v[156:157], 0, s[26:27]
	v_lshl_add_u64 v[158:159], v[158:159], 0, s[26:27]
	v_lshl_add_u64 v[160:161], v[160:161], 0, s[26:27]
	v_lshl_add_u64 v[162:163], v[162:163], 0, s[26:27]
	v_lshl_add_u64 v[164:165], v[164:165], 0, s[26:27]
	v_lshl_add_u64 v[166:167], v[166:167], 0, s[26:27]
	v_lshl_add_u64 v[168:169], v[168:169], 0, s[26:27]
	v_lshl_add_u64 v[170:171], v[170:171], 0, s[26:27]
	v_lshl_add_u64 v[172:173], v[172:173], 0, s[42:43]
	s_cmp_lt_i32 s14, s76
	v_lshl_add_u64 v[174:175], v[174:175], 0, s[44:45]
	s_cbranch_scc0 .LBB0_1127

; template <int OFF = 0, class V> __device__ __forceinline__ void st_wt16(void* p, V v) { static_assert(sizeof(V) == 16, ""); asm volatile("global_store_dwordx4 %0, %1, off offset:%2 sc1\n\ts_nop 1" :: "v"(p), "v"(v), "i"(OFF)); }
; template <int OFF = 0, class V> __device__ __forceinline__ void st_wt8(void* p, V v) { static_assert(sizeof(V) == 8, ""); asm volatile("global_store_dwordx2 %0, %1, off offset:%2 sc1\n\ts_nop 1" :: "v"(p), "v"(v), "i"(OFF)); }
; __device__ __forceinline__ unsigned pk2(float lo, float hi) { return pg8::cvt_pk_bf16(lo, hi); }
; __device__ __forceinline__ void resid_rows(bf16* __restrict__ XB, const bf16* __restrict__ Y, const float* __restrict__ PART, const float* __restrict__ g, float* __restrict__ RS, ...
;     ...
;             ss += (o.x * o.x + o.y * o.y) + (o.z * o.z + o.w * o.w); ov[j] = o; am = fmaxf(fmaxf(am, fmaxf(fabsf(o.x), fabsf(o.y))), fmaxf(fabsf(o.z), fabsf(o.w)));
;             if (outf) st_wt16(outf + (size_t)m * DM + c, o); else { v2u ob; ob.x = pk2(o.x, o.y); ob.y = pk2(o.z, o.w); st_wt8(xrow + c, ob); } }
;         if (XQ) {
;             am = fmaxf(wave_max(am), 1e-20f); const float qs = 127.0f / am;
.LBB0_1105:
	s_andn2_b64 vcc, exec, s[40:41]
	s_cbranch_vccnz .LBB0_1109
	v_max_f32_e64 v176, |v65|, |v65|
	v_max_f32_e64 v177, |v64|, |v64|
	v_max_f32_e32 v176, v177, v176
	v_max_f32_e64 v177, |v67|, |v67|
	v_max_f32_e64 v178, |v66|, |v66|
	v_max_f32_e32 v177, v178, v177
	v_max3_f32 v176, v176, 0, v177
	v_max_f32_e64 v177, |v69|, |v69|
	v_max_f32_e64 v178, |v68|, |v68|
	v_max_f32_e32 v177, v178, v177
	v_max_f32_e64 v178, |v71|, |v71|
	v_max_f32_e64 v179, |v70|, |v70|
	v_max_f32_e32 v178, v179, v178
	v_max3_f32 v176, v176, v177, v178
	v_max_f32_e64 v177, |v73|, |v73|
	v_max_f32_e64 v178, |v72|, |v72|
	v_max_f32_e32 v177, v178, v177
	v_max_f32_e64 v178, |v75|, |v75|
	v_max_f32_e64 v179, |v74|, |v74|
	v_max_f32_e32 v178, v179, v178
	v_max3_f32 v176, v176, v177, v178
	v_max_f32_e64 v177, |v77|, |v77|
	v_max_f32_e64 v178, |v76|, |v76|
	v_max_f32_e32 v177, v178, v177
	v_max_f32_e64 v178, |v79|, |v79|
	v_max_f32_e64 v179, |v78|, |v78|
	v_max_f32_e32 v178, v179, v178
	v_max3_f32 v176, v176, v177, v178
	v_max_f32_e64 v177, |v81|, |v81|
	v_max_f32_e64 v178, |v80|, |v80|
	v_max_f32_e32 v177, v178, v177
	v_max_f32_e64 v178, |v83|, |v83|
	v_max_f32_e64 v179, |v82|, |v82|
	v_max_f32_e32 v178, v179, v178
	v_max3_f32 v176, v176, v177, v178
	v_max_f32_e64 v177, |v85|, |v85|
	v_max_f32_e64 v178, |v84|, |v84|
	v_max_f32_e32 v177, v178, v177
	v_max_f32_e64 v178, |v87|, |v87|
	v_max_f32_e64 v179, |v86|, |v86|
	v_max_f32_e32 v178, v179, v178
	v_max3_f32 v176, v176, v177, v178
	v_max_f32_e64 v177, |v89|, |v89|
	v_max_f32_e64 v178, |v88|, |v88|
	v_max_f32_e32 v177, v178, v177
	v_max_f32_e64 v178, |v91|, |v91|
	v_max_f32_e64 v179, |v90|, |v90|
	v_max_f32_e32 v178, v179, v178
	v_max3_f32 v176, v176, v177, v178
	v_max_f32_e64 v177, |v93|, |v93|
	v_max_f32_e64 v178, |v92|, |v92|
	v_max_f32_e32 v177, v178, v177
	v_max_f32_e64 v178, |v95|, |v95|
	v_max_f32_e64 v179, |v94|, |v94|
	v_max_f32_e32 v178, v179, v178
	v_max3_f32 v176, v176, v177, v178
	v_max_f32_e64 v177, |v97|, |v97|
	v_max_f32_e64 v178, |v96|, |v96|
	v_max_f32_e32 v177, v178, v177
	v_max_f32_e64 v178, |v99|, |v99|
	v_max_f32_e64 v179, |v98|, |v98|
	v_max_f32_e32 v178, v179, v178
	v_max3_f32 v176, v176, v177, v178
	v_max_f32_e64 v177, |v101|, |v101|
	v_max_f32_e64 v178, |v100|, |v100|
	v_max_f32_e32 v177, v178, v177
	v_max_f32_e64 v178, |v103|, |v103|
	v_max_f32_e64 v179, |v102|, |v102|
	v_max_f32_e32 v178, v179, v178
	v_max3_f32 v176, v176, v177, v178
	v_max_f32_e64 v177, |v105|, |v105|
	v_max_f32_e64 v178, |v104|, |v104|
	v_max_f32_e32 v177, v178, v177
	v_max_f32_e64 v178, |v107|, |v107|
	v_max_f32_e64 v179, |v106|, |v106|
	v_max_f32_e32 v178, v179, v178
	v_max3_f32 v176, v176, v177, v178
	v_max_f32_e64 v177, |v109|, |v109|
	v_max_f32_e64 v178, |v108|, |v108|
	v_max_f32_e32 v177, v178, v177
	v_max_f32_e64 v178, |v111|, |v111|
	v_max_f32_e64 v179, |v110|, |v110|
	v_max_f32_e32 v178, v179, v178
	v_max3_f32 v176, v176, v177, v178
	v_max_f32_e64 v177, |v113|, |v113|
	v_max_f32_e64 v178, |v112|, |v112|
	v_max_f32_e32 v177, v178, v177
	v_max_f32_e64 v178, |v115|, |v115|
	v_max_f32_e64 v179, |v114|, |v114|
	v_max_f32_e32 v178, v179, v178
	v_max3_f32 v176, v176, v177, v178
	v_max_f32_e64 v177, |v117|, |v117|
	v_max_f32_e64 v178, |v116|, |v116|
	v_max_f32_e32 v177, v178, v177
	v_max_f32_e64 v178, |v119|, |v119|
	v_max_f32_e64 v179, |v118|, |v118|
	v_max_f32_e32 v178, v179, v178
	v_max3_f32 v176, v176, v177, v178
	v_max_f32_e64 v177, |v121|, |v121|
	v_max_f32_e64 v178, |v120|, |v120|
	v_max_f32_e32 v177, v178, v177
	v_max_f32_e64 v178, |v123|, |v123|
	v_max_f32_e64 v179, |v122|, |v122|
	v_max_f32_e32 v178, v179, v178
	v_max3_f32 v176, v176, v177, v178
	v_max_f32_e64 v177, |v125|, |v125|
	v_max_f32_e64 v178, |v124|, |v124|
	v_max_f32_e32 v177, v178, v177
	v_max_f32_e64 v178, |v127|, |v127|
	v_max_f32_e64 v179, |v126|, |v126|
	v_max_f32_e32 v178, v179, v178
	v_max3_f32 v176, v176, v177, v178
	ds_swizzle_b32 v177, v176 offset:swizzle(SWAP,1)
	s_mov_b32 s4, 0x1e3ce508
	s_mov_b32 s7, 0x42fe0000
	s_mov_b64 s[10:11], 0x100
	s_waitcnt lgkmcnt(0)
	v_max_f32_e32 v177, v177, v177
	v_max_f32_e32 v176, v176, v177
	ds_swizzle_b32 v177, v176 offset:swizzle(SWAP,2)
	s_waitcnt lgkmcnt(0)
	v_max_f32_e32 v177, v177, v177
	v_max_f32_e32 v176, v176, v177
	ds_swizzle_b32 v177, v176 offset:swizzle(SWAP,4)
	s_waitcnt lgkmcnt(0)
	v_max_f32_e32 v177, v177, v177
	v_max_f32_e32 v176, v176, v177
	ds_swizzle_b32 v177, v176 offset:swizzle(SWAP,8)
	s_waitcnt lgkmcnt(0)
	v_max_f32_e32 v177, v177, v177
	v_max_f32_e32 v176, v176, v177
	ds_swizzle_b32 v177, v176 offset:swizzle(SWAP,16)
	s_waitcnt lgkmcnt(0)
; __device__ __forceinline__ void st_wt4(void* p, unsigned v) { asm volatile("global_store_dword %0, %1, off sc1\n\ts_nop 1" :: "v"(p), "v"(v)); }
; __device__ __forceinline__ void resid_rows(bf16* __restrict__ XB, const bf16* __restrict__ Y, const float* __restrict__ PART, const float* __restrict__ g, float* __restrict__ RS, ...
;     ...
;             am = fmaxf(wave_max(am), 1e-20f); const float qs = 127.0f / am;
; #pragma unroll
;             for (int j = 0; j < 16; ++j) { const int q0 = (int)rintf(ov[j].x * qs), q1 = (int)rintf(ov[j].y * qs), q2 = (int)rintf(ov[j].z * qs), q3 = (int)rintf(ov[j].w * qs);
;                 st_wt4(XQ + (size_t)m * (DM / 4) + lane + 64 * j, ((unsigned)q0 & 255u) | (((unsigned)q1 & 255u) << 8) | (((unsigned)q2 & 255u) << 16) | ((unsigned)q3 << 24)); }
	v_max_f32_e32 v177, v177, v177
	v_max_f32_e32 v176, v176, v177
	v_mov_b32_e32 v177, v176
	s_nop 1
	v_permlane32_swap_b32_e32 v176, v177
	v_max3_f32 v176, v176, v177, s4
	v_div_scale_f32 v177, s[4:5], v176, v176, s7
	v_rcp_f32_e32 v178, v177
	s_mov_b32 s4, 0x40c0c00
	v_fma_f32 v179, -v177, v178, 1.0
	v_fmac_f32_e32 v178, v179, v178
	v_div_scale_f32 v179, vcc, s7, v176, s7
	v_mul_f32_e32 v180, v179, v178
	v_fma_f32 v181, -v177, v180, v179
	v_fmac_f32_e32 v180, v181, v178
	v_fma_f32 v177, -v177, v180, v179
	v_div_fmas_f32 v177, v177, v178, v180
	v_div_fixup_f32 v177, v177, v176, s7
	v_mul_f32_e32 v179, v65, v177
	v_mul_f32_e32 v178, v64, v177
	v_rndne_f32_e32 v179, v179
	v_mul_f32_e32 v180, v66, v177
	v_mul_f32_e32 v181, v67, v177
	v_rndne_f32_e32 v178, v178
	v_cvt_i32_f32_e32 v179, v179
	v_rndne_f32_e32 v180, v180
	v_rndne_f32_e32 v181, v181
	v_cvt_i32_f32_e32 v178, v178
	v_cvt_i32_f32_sdwa v180, v180 dst_sel:WORD_1 dst_unused:UNUSED_PAD src0_sel:DWORD
	v_cvt_i32_f32_e32 v181, v181
	v_lshlrev_b32_e32 v179, 8, v179
	v_and_b32_e32 v179, 0xff00, v179
	v_and_b32_e32 v180, 0xff0000, v180
	v_perm_b32 v178, v181, v178, s4
	v_or3_b32 v178, v178, v179, v180
	global_store_dword v[172:173], v178, off
	s_nop 1
	v_mul_f32_e32 v178, v68, v177
	v_rndne_f32_e32 v178, v178
	v_cvt_i32_f32_e32 v180, v178
	v_mul_f32_e32 v178, v69, v177
	v_rndne_f32_e32 v178, v178
	v_cvt_i32_f32_e32 v181, v178
	v_mul_f32_e32 v178, v70, v177
	v_rndne_f32_e32 v178, v178
	v_cvt_i32_f32_sdwa v182, v178 dst_sel:WORD_1 dst_unused:UNUSED_PAD src0_sel:DWORD
	v_mul_f32_e32 v178, v71, v177
	v_rndne_f32_e32 v178, v178
	v_cvt_i32_f32_e32 v183, v178
	v_lshlrev_b32_e32 v181, 8, v181
	v_lshl_add_u64 v[178:179], v[172:173], 0, s[10:11]
	v_and_b32_e32 v181, 0xff00, v181
	v_and_b32_e32 v182, 0xff0000, v182
	v_perm_b32 v180, v183, v180, s4
	v_or3_b32 v180, v180, v181, v182
	global_store_dword v[178:179], v180, off
	s_nop 1
	v_mul_f32_e32 v178, v72, v177
	v_rndne_f32_e32 v178, v178
	v_cvt_i32_f32_e32 v180, v178
	v_mul_f32_e32 v178, v73, v177
	v_rndne_f32_e32 v178, v178
	v_cvt_i32_f32_e32 v181, v178
	v_mul_f32_e32 v178, v74, v177
	v_rndne_f32_e32 v178, v178
	v_cvt_i32_f32_sdwa v182, v178 dst_sel:WORD_1 dst_unused:UNUSED_PAD src0_sel:DWORD
	v_mul_f32_e32 v178, v75, v177
	v_rndne_f32_e32 v178, v178
	v_cvt_i32_f32_e32 v183, v178
	s_mov_b64 s[10:11], 0x200
	v_lshlrev_b32_e32 v181, 8, v181
	v_lshl_add_u64 v[178:179], v[172:173], 0, s[10:11]
	v_and_b32_e32 v181, 0xff00, v181
	v_and_b32_e32 v182, 0xff0000, v182
	v_perm_b32 v180, v183, v180, s4
	v_or3_b32 v180, v180, v181, v182
	global_store_dword v[178:179], v180, off
	s_nop 1
	v_mul_f32_e32 v178, v76, v177
	v_rndne_f32_e32 v178, v178
	v_cvt_i32_f32_e32 v180, v178
	v_mul_f32_e32 v178, v77, v177
	v_rndne_f32_e32 v178, v178
	v_cvt_i32_f32_e32 v181, v178
	v_mul_f32_e32 v178, v78, v177
	v_rndne_f32_e32 v178, v178
	v_cvt_i32_f32_sdwa v182, v178 dst_sel:WORD_1 dst_unused:UNUSED_PAD src0_sel:DWORD
	v_mul_f32_e32 v178, v79, v177
	v_rndne_f32_e32 v178, v178
	v_cvt_i32_f32_e32 v183, v178
	s_mov_b64 s[10:11], 0x300
	v_lshlrev_b32_e32 v181, 8, v181
	v_lshl_add_u64 v[178:179], v[172:173], 0, s[10:11]
	v_and_b32_e32 v181, 0xff00, v181
	v_and_b32_e32 v182, 0xff0000, v182
	v_perm_b32 v180, v183, v180, s4
	v_or3_b32 v180, v180, v181, v182
	global_store_dword v[178:179], v180, off
	s_nop 1
	v_mul_f32_e32 v178, v80, v177
	v_rndne_f32_e32 v178, v178
	v_cvt_i32_f32_e32 v180, v178
	v_mul_f32_e32 v178, v81, v177
	v_rndne_f32_e32 v178, v178
	v_cvt_i32_f32_e32 v181, v178
	v_mul_f32_e32 v178, v82, v177
	v_rndne_f32_e32 v178, v178
	v_cvt_i32_f32_sdwa v182, v178 dst_sel:WORD_1 dst_unused:UNUSED_PAD src0_sel:DWORD
	v_mul_f32_e32 v178, v83, v177
	v_rndne_f32_e32 v178, v178
	v_cvt_i32_f32_e32 v183, v178
	s_mov_b64 s[10:11], 0x400
	v_lshlrev_b32_e32 v181, 8, v181
	v_lshl_add_u64 v[178:179], v[172:173], 0, s[10:11]
	v_and_b32_e32 v181, 0xff00, v181
	v_and_b32_e32 v182, 0xff0000, v182
	v_perm_b32 v180, v183, v180, s4
	v_or3_b32 v180, v180, v181, v182
	global_store_dword v[178:179], v180, off
	s_nop 1
	v_mul_f32_e32 v178, v84, v177
	v_rndne_f32_e32 v178, v178
	v_cvt_i32_f32_e32 v180, v178
	v_mul_f32_e32 v178, v85, v177
	v_rndne_f32_e32 v178, v178
	v_cvt_i32_f32_e32 v181, v178
	v_mul_f32_e32 v178, v86, v177
	v_rndne_f32_e32 v178, v178
	v_cvt_i32_f32_sdwa v182, v178 dst_sel:WORD_1 dst_unused:UNUSED_PAD src0_sel:DWORD
	v_mul_f32_e32 v178, v87, v177
	v_rndne_f32_e32 v178, v178
	v_cvt_i32_f32_e32 v183, v178
	s_mov_b64 s[10:11], 0x500
	v_lshlrev_b32_e32 v181, 8, v181
	v_lshl_add_u64 v[178:179], v[172:173], 0, s[10:11]
	v_and_b32_e32 v181, 0xff00, v181
	v_and_b32_e32 v182, 0xff0000, v182
	v_perm_b32 v180, v183, v180, s4
	v_or3_b32 v180, v180, v181, v182
	global_store_dword v[178:179], v180, off
	s_nop 1
	v_mul_f32_e32 v178, v88, v177
	v_rndne_f32_e32 v178, v178
	v_cvt_i32_f32_e32 v180, v178
	v_mul_f32_e32 v178, v89, v177
	v_rndne_f32_e32 v178, v178
	v_cvt_i32_f32_e32 v181, v178
	v_mul_f32_e32 v178, v90, v177
	v_rndne_f32_e32 v178, v178
	v_cvt_i32_f32_sdwa v182, v178 dst_sel:WORD_1 dst_unused:UNUSED_PAD src0_sel:DWORD
	v_mul_f32_e32 v178, v91, v177
	v_rndne_f32_e32 v178, v178
	v_cvt_i32_f32_e32 v183, v178
	s_mov_b64 s[10:11], 0x600
	v_lshlrev_b32_e32 v181, 8, v181
	v_lshl_add_u64 v[178:179], v[172:173], 0, s[10:11]
	v_and_b32_e32 v181, 0xff00, v181
	v_and_b32_e32 v182, 0xff0000, v182
	v_perm_b32 v180, v183, v180, s4
	v_or3_b32 v180, v180, v181, v182
	global_store_dword v[178:179], v180, off
	s_nop 1
	v_mul_f32_e32 v178, v92, v177
	v_rndne_f32_e32 v178, v178
	v_cvt_i32_f32_e32 v180, v178
	v_mul_f32_e32 v178, v93, v177
	v_rndne_f32_e32 v178, v178
	v_cvt_i32_f32_e32 v181, v178
	v_mul_f32_e32 v178, v94, v177
; __device__ __forceinline__ void st_wt4(void* p, unsigned v) { asm volatile("global_store_dword %0, %1, off sc1\n\ts_nop 1" :: "v"(p), "v"(v)); }
; __device__ __forceinline__ void resid_rows(bf16* __restrict__ XB, const bf16* __restrict__ Y, const float* __restrict__ PART, const float* __restrict__ g, float* __restrict__ RS, ...
;     ...
;             for (int j = 0; j < 16; ++j) { const int q0 = (int)rintf(ov[j].x * qs), q1 = (int)rintf(ov[j].y * qs), q2 = (int)rintf(ov[j].z * qs), q3 = (int)rintf(ov[j].w * qs);
;                 st_wt4(XQ + (size_t)m * (DM / 4) + lane + 64 * j, ((unsigned)q0 & 255u) | (((unsigned)q1 & 255u) << 8) | (((unsigned)q2 & 255u) << 16) | ((unsigned)q3 << 24)); }
;             if (lane == 0) AS[m] = am * (1.0f / 127.0f); }
	v_rndne_f32_e32 v178, v178
	v_cvt_i32_f32_sdwa v182, v178 dst_sel:WORD_1 dst_unused:UNUSED_PAD src0_sel:DWORD
	v_mul_f32_e32 v178, v95, v177
	v_rndne_f32_e32 v178, v178
	v_cvt_i32_f32_e32 v183, v178
	s_mov_b64 s[10:11], 0x700
	v_lshlrev_b32_e32 v181, 8, v181
	v_lshl_add_u64 v[178:179], v[172:173], 0, s[10:11]
	v_and_b32_e32 v181, 0xff00, v181
	v_and_b32_e32 v182, 0xff0000, v182
	v_perm_b32 v180, v183, v180, s4
	v_or3_b32 v180, v180, v181, v182
	global_store_dword v[178:179], v180, off
	s_nop 1
	v_mul_f32_e32 v178, v96, v177
	v_rndne_f32_e32 v178, v178
	v_cvt_i32_f32_e32 v180, v178
	v_mul_f32_e32 v178, v97, v177
	v_rndne_f32_e32 v178, v178
	v_cvt_i32_f32_e32 v181, v178
	v_mul_f32_e32 v178, v98, v177
	v_rndne_f32_e32 v178, v178
	v_cvt_i32_f32_sdwa v182, v178 dst_sel:WORD_1 dst_unused:UNUSED_PAD src0_sel:DWORD
	v_mul_f32_e32 v178, v99, v177
	v_rndne_f32_e32 v178, v178
	v_cvt_i32_f32_e32 v183, v178
	s_mov_b64 s[10:11], 0x800
	v_lshlrev_b32_e32 v181, 8, v181
	v_lshl_add_u64 v[178:179], v[172:173], 0, s[10:11]
	v_and_b32_e32 v181, 0xff00, v181
	v_and_b32_e32 v182, 0xff0000, v182
	v_perm_b32 v180, v183, v180, s4
	v_or3_b32 v180, v180, v181, v182
	global_store_dword v[178:179], v180, off
	s_nop 1
	v_mul_f32_e32 v178, v100, v177
	v_rndne_f32_e32 v178, v178
	v_cvt_i32_f32_e32 v180, v178
	v_mul_f32_e32 v178, v101, v177
	v_rndne_f32_e32 v178, v178
	v_cvt_i32_f32_e32 v181, v178
	v_mul_f32_e32 v178, v102, v177
	v_rndne_f32_e32 v178, v178
	v_cvt_i32_f32_sdwa v182, v178 dst_sel:WORD_1 dst_unused:UNUSED_PAD src0_sel:DWORD
	v_mul_f32_e32 v178, v103, v177
	v_rndne_f32_e32 v178, v178
	v_cvt_i32_f32_e32 v183, v178
	s_mov_b64 s[10:11], 0x900
	v_lshlrev_b32_e32 v181, 8, v181
	v_lshl_add_u64 v[178:179], v[172:173], 0, s[10:11]
	v_and_b32_e32 v181, 0xff00, v181
	v_and_b32_e32 v182, 0xff0000, v182
	v_perm_b32 v180, v183, v180, s4
	v_or3_b32 v180, v180, v181, v182
	global_store_dword v[178:179], v180, off
	s_nop 1
	v_mul_f32_e32 v178, v104, v177
	v_rndne_f32_e32 v178, v178
	v_cvt_i32_f32_e32 v180, v178
	v_mul_f32_e32 v178, v105, v177
	v_rndne_f32_e32 v178, v178
	v_cvt_i32_f32_e32 v181, v178
	v_mul_f32_e32 v178, v106, v177
	v_rndne_f32_e32 v178, v178
	v_cvt_i32_f32_sdwa v182, v178 dst_sel:WORD_1 dst_unused:UNUSED_PAD src0_sel:DWORD
	v_mul_f32_e32 v178, v107, v177
	v_rndne_f32_e32 v178, v178
	v_cvt_i32_f32_e32 v183, v178
	s_mov_b64 s[10:11], 0xa00
	v_lshlrev_b32_e32 v181, 8, v181
	v_lshl_add_u64 v[178:179], v[172:173], 0, s[10:11]
	v_and_b32_e32 v181, 0xff00, v181
	v_and_b32_e32 v182, 0xff0000, v182
	v_perm_b32 v180, v183, v180, s4
	v_or3_b32 v180, v180, v181, v182
	global_store_dword v[178:179], v180, off
	s_nop 1
	v_mul_f32_e32 v178, v108, v177
	v_rndne_f32_e32 v178, v178
	v_cvt_i32_f32_e32 v180, v178
	v_mul_f32_e32 v178, v109, v177
	v_rndne_f32_e32 v178, v178
	v_cvt_i32_f32_e32 v181, v178
	v_mul_f32_e32 v178, v110, v177
	v_rndne_f32_e32 v178, v178
	v_cvt_i32_f32_sdwa v182, v178 dst_sel:WORD_1 dst_unused:UNUSED_PAD src0_sel:DWORD
	v_mul_f32_e32 v178, v111, v177
	v_rndne_f32_e32 v178, v178
	v_cvt_i32_f32_e32 v183, v178
	s_mov_b64 s[10:11], 0xb00
	v_lshlrev_b32_e32 v181, 8, v181
	v_lshl_add_u64 v[178:179], v[172:173], 0, s[10:11]
	v_and_b32_e32 v181, 0xff00, v181
	v_and_b32_e32 v182, 0xff0000, v182
	v_perm_b32 v180, v183, v180, s4
	v_or3_b32 v180, v180, v181, v182
	global_store_dword v[178:179], v180, off
	s_nop 1
	v_mul_f32_e32 v178, v112, v177
	v_rndne_f32_e32 v178, v178
	v_cvt_i32_f32_e32 v180, v178
	v_mul_f32_e32 v178, v113, v177
	v_rndne_f32_e32 v178, v178
	v_cvt_i32_f32_e32 v181, v178
	v_mul_f32_e32 v178, v114, v177
	v_rndne_f32_e32 v178, v178
	v_cvt_i32_f32_sdwa v182, v178 dst_sel:WORD_1 dst_unused:UNUSED_PAD src0_sel:DWORD
	v_mul_f32_e32 v178, v115, v177
	v_rndne_f32_e32 v178, v178
	v_cvt_i32_f32_e32 v183, v178
	s_mov_b64 s[10:11], 0xc00
	v_lshlrev_b32_e32 v181, 8, v181
	v_lshl_add_u64 v[178:179], v[172:173], 0, s[10:11]
	v_and_b32_e32 v181, 0xff00, v181
	v_and_b32_e32 v182, 0xff0000, v182
	v_perm_b32 v180, v183, v180, s4
	v_or3_b32 v180, v180, v181, v182
	global_store_dword v[178:179], v180, off
	s_nop 1
	v_mul_f32_e32 v178, v116, v177
	v_rndne_f32_e32 v178, v178
	v_cvt_i32_f32_e32 v180, v178
	v_mul_f32_e32 v178, v117, v177
	v_rndne_f32_e32 v178, v178
	v_cvt_i32_f32_e32 v181, v178
	v_mul_f32_e32 v178, v118, v177
	v_rndne_f32_e32 v178, v178
	v_cvt_i32_f32_sdwa v182, v178 dst_sel:WORD_1 dst_unused:UNUSED_PAD src0_sel:DWORD
	v_mul_f32_e32 v178, v119, v177
	v_rndne_f32_e32 v178, v178
	v_cvt_i32_f32_e32 v183, v178
	s_mov_b64 s[10:11], 0xd00
	v_lshlrev_b32_e32 v181, 8, v181
	v_lshl_add_u64 v[178:179], v[172:173], 0, s[10:11]
	v_and_b32_e32 v181, 0xff00, v181
	v_and_b32_e32 v182, 0xff0000, v182
	v_perm_b32 v180, v183, v180, s4
	v_or3_b32 v180, v180, v181, v182
	global_store_dword v[178:179], v180, off
	s_nop 1
	v_mul_f32_e32 v178, v120, v177
	v_rndne_f32_e32 v178, v178
	v_cvt_i32_f32_e32 v180, v178
	v_mul_f32_e32 v178, v121, v177
	v_rndne_f32_e32 v178, v178
	v_cvt_i32_f32_e32 v181, v178
	v_mul_f32_e32 v178, v122, v177
	v_rndne_f32_e32 v178, v178
	v_cvt_i32_f32_sdwa v182, v178 dst_sel:WORD_1 dst_unused:UNUSED_PAD src0_sel:DWORD
	v_mul_f32_e32 v178, v123, v177
	v_rndne_f32_e32 v178, v178
	v_cvt_i32_f32_e32 v183, v178
	s_mov_b64 s[10:11], 0xe00
	v_lshlrev_b32_e32 v181, 8, v181
	v_lshl_add_u64 v[178:179], v[172:173], 0, s[10:11]
	v_and_b32_e32 v181, 0xff00, v181
	v_and_b32_e32 v182, 0xff0000, v182
	v_perm_b32 v180, v183, v180, s4
	v_or3_b32 v180, v180, v181, v182
	global_store_dword v[178:179], v180, off
	s_nop 1
	v_mul_f32_e32 v178, v124, v177
	v_rndne_f32_e32 v178, v178
	v_cvt_i32_f32_e32 v180, v178
	v_mul_f32_e32 v178, v125, v177
	v_rndne_f32_e32 v178, v178
	v_cvt_i32_f32_e32 v181, v178
	v_mul_f32_e32 v178, v126, v177
	v_mul_f32_e32 v177, v127, v177
	v_rndne_f32_e32 v178, v178
	v_rndne_f32_e32 v177, v177
	v_cvt_i32_f32_sdwa v182, v178 dst_sel:WORD_1 dst_unused:UNUSED_PAD src0_sel:DWORD
	v_cvt_i32_f32_e32 v177, v177
	v_lshlrev_b32_e32 v181, 8, v181
	s_mov_b64 s[10:11], 0xf00
	v_and_b32_e32 v181, 0xff00, v181
	v_and_b32_e32 v182, 0xff0000, v182
	v_perm_b32 v177, v177, v180, s4
	v_lshl_add_u64 v[178:179], v[172:173], 0, s[10:11]
	v_or3_b32 v177, v177, v181, v182
	global_store_dword v[178:179], v177, off
	s_nop 1
	s_and_saveexec_b64 s[4:5], s[2:3]
	s_cbranch_execz .LBB0_1108
	s_add_u32 s10, s8, s22
	v_mul_f32_e32 v176, 0x3c010204, v176
	s_addc_u32 s11, s9, s23
	v_mov_b32_e32 v177, 0x110000
	global_store_dword v177, v176, s[10:11]
